# retention out-unit epilogue (R1,R3): gate loads/stores paired into dwordx4 via v_permlane32_swap; plus S5 scan register transpose and conv_part moved to GLU-phase idle workgroups
# speedup vs baseline: 1.0260x; 1.0082x over previous
.LBB0_562:
	v_mul_f32_e32 v132, v113, v113
	v_fmac_f32_e32 v132, v112, v112
	v_fmac_f32_e32 v132, v114, v114
	v_fmac_f32_e32 v132, v115, v115
	v_fmac_f32_e32 v132, v116, v116
	v_fmac_f32_e32 v132, v117, v117
	v_fmac_f32_e32 v132, v118, v118
	v_fmac_f32_e32 v132, v119, v119
	v_fmac_f32_e32 v132, v120, v120
	v_fmac_f32_e32 v132, v121, v121
	v_fmac_f32_e32 v132, v122, v122
	v_fmac_f32_e32 v132, v123, v123
	v_fmac_f32_e32 v132, v124, v124
	v_fmac_f32_e32 v132, v125, v125
	v_fmac_f32_e32 v132, v126, v126
	v_fmac_f32_e32 v132, v127, v127
	v_fmac_f32_e32 v132, v96, v96
	v_fmac_f32_e32 v132, v97, v97
	v_fmac_f32_e32 v132, v98, v98
	v_fmac_f32_e32 v132, v99, v99
	v_fmac_f32_e32 v132, v100, v100
	v_fmac_f32_e32 v132, v101, v101
	v_fmac_f32_e32 v132, v102, v102
	v_fmac_f32_e32 v132, v103, v103
	v_fmac_f32_e32 v132, v104, v104
	v_fmac_f32_e32 v132, v105, v105
	v_fmac_f32_e32 v132, v106, v106
	v_fmac_f32_e32 v132, v107, v107
	v_fmac_f32_e32 v132, v108, v108
	v_fmac_f32_e32 v132, v109, v109
	v_fmac_f32_e32 v132, v110, v110
	v_fmac_f32_e32 v132, v111, v111
	v_fmac_f32_e32 v132, v80, v80
	v_fmac_f32_e32 v132, v81, v81
	v_fmac_f32_e32 v132, v82, v82
	v_fmac_f32_e32 v132, v83, v83
	v_fmac_f32_e32 v132, v84, v84
	v_fmac_f32_e32 v132, v85, v85
	v_fmac_f32_e32 v132, v86, v86
	v_fmac_f32_e32 v132, v87, v87
	v_fmac_f32_e32 v132, v88, v88
	v_fmac_f32_e32 v132, v89, v89
	v_fmac_f32_e32 v132, v90, v90
	v_fmac_f32_e32 v132, v91, v91
	v_fmac_f32_e32 v132, v92, v92
	v_fmac_f32_e32 v132, v93, v93
	v_fmac_f32_e32 v132, v94, v94
	v_fmac_f32_e32 v132, v95, v95
	v_fmac_f32_e32 v132, v64, v64
	v_fmac_f32_e32 v132, v65, v65
	v_fmac_f32_e32 v132, v66, v66
	v_fmac_f32_e32 v132, v67, v67
	v_fmac_f32_e32 v132, v68, v68
	v_fmac_f32_e32 v132, v69, v69
	v_fmac_f32_e32 v132, v70, v70
	v_fmac_f32_e32 v132, v71, v71
	v_fmac_f32_e32 v132, v72, v72
	v_fmac_f32_e32 v132, v73, v73
	v_fmac_f32_e32 v132, v74, v74
	v_fmac_f32_e32 v132, v75, v75
	v_fmac_f32_e32 v132, v76, v76
	v_fmac_f32_e32 v132, v77, v77
	v_fmac_f32_e32 v132, v78, v78
	v_fmac_f32_e32 v132, v79, v79
	v_fmac_f32_e32 v132, v48, v48
	v_fmac_f32_e32 v132, v49, v49
	v_fmac_f32_e32 v132, v50, v50
	v_fmac_f32_e32 v132, v51, v51
	v_fmac_f32_e32 v132, v52, v52
	v_fmac_f32_e32 v132, v53, v53
	v_fmac_f32_e32 v132, v54, v54
	v_fmac_f32_e32 v132, v55, v55
	v_fmac_f32_e32 v132, v56, v56
	s_lshl_b32 s8, s16, 5
	v_fmac_f32_e32 v132, v57, v57
	s_and_b32 s8, s8, 0xffffff00
	v_fmac_f32_e32 v132, v58, v58
	v_fmac_f32_e32 v132, v59, v59
	v_add_u32_e32 v128, s8, v209
	v_fmac_f32_e32 v132, v60, v60
	v_ashrrev_i32_e32 v129, 31, v128
	v_fmac_f32_e32 v132, v61, v61
	v_lshlrev_b64 v[128:129], 12, v[128:129]
	v_fmac_f32_e32 v132, v62, v62
	v_lshl_add_u64 v[128:129], s[4:5], 0, v[128:129]
	s_lshl_b32 s96, s24, 9
	v_fmac_f32_e32 v132, v63, v63
	v_lshl_add_u64 v[128:129], v[128:129], 0, s[96:97]
	s_movk_i32 s8, 0xe0
	v_ashrrev_i32_e32 v209, 31, v208
	v_fmac_f32_e32 v132, v32, v32
	s_load_dwordx2 s[8:9], s[10:11], s8
	s_waitcnt lgkmcnt(0)
	v_lshl_add_u64 v[144:145], v[208:209], 1, v[128:129]
	v_lshl_add_u64 v[206:207], v[208:209], 1, v[144:145]
	v_fmac_f32_e32 v132, v33, v33
	global_load_dwordx4 v[188:191], v[206:207], off offset:0
	global_load_dwordx4 v[192:195], v[206:207], off offset:32
	global_load_dwordx4 v[196:199], v[206:207], off offset:64
	global_load_dwordx4 v[202:205], v[206:207], off offset:96
	global_load_dwordx4 v[210:213], v[206:207], off offset:128
	global_load_dwordx4 v[216:219], v[206:207], off offset:160
	global_load_dwordx4 v[220:223], v[206:207], off offset:192
	global_load_dwordx4 v[224:227], v[206:207], off offset:224
	v_fmac_f32_e32 v132, v34, v34
	v_fmac_f32_e32 v132, v35, v35
	v_fmac_f32_e32 v132, v36, v36
	v_fmac_f32_e32 v132, v37, v37
	v_fmac_f32_e32 v132, v38, v38
	v_fmac_f32_e32 v132, v39, v39
	v_fmac_f32_e32 v132, v40, v40
	v_fmac_f32_e32 v132, v41, v41
	v_fmac_f32_e32 v132, v42, v42
	v_fmac_f32_e32 v132, v43, v43
	v_fmac_f32_e32 v132, v44, v44
	s_add_u32 s8, s8, s14
	v_fmac_f32_e32 v132, v45, v45
	s_addc_u32 s9, s9, s15
	s_lshl_b32 s17, s24, 10
	v_fmac_f32_e32 v132, v46, v46
	s_add_u32 s8, s8, s17
	v_fmac_f32_e32 v132, v47, v47
	s_addc_u32 s9, s9, 0
	v_fmac_f32_e32 v132, v16, v16
	v_lshl_add_u64 v[146:147], v[208:209], 2, s[8:9]
	v_fmac_f32_e32 v132, v17, v17
	global_load_dwordx4 v[158:161], v[146:147], off
	global_load_dwordx4 v[162:165], v[146:147], off offset:32
	v_fmac_f32_e32 v132, v18, v18
	v_fmac_f32_e32 v132, v19, v19
	v_fmac_f32_e32 v132, v20, v20
	v_fmac_f32_e32 v132, v21, v21
	v_fmac_f32_e32 v132, v22, v22
	v_fmac_f32_e32 v132, v23, v23
	v_fmac_f32_e32 v132, v24, v24
	v_fmac_f32_e32 v132, v25, v25
	v_fmac_f32_e32 v132, v26, v26
	v_fmac_f32_e32 v132, v27, v27
	v_fmac_f32_e32 v132, v28, v28
	v_fmac_f32_e32 v132, v29, v29
	v_fmac_f32_e32 v132, v30, v30
	v_fmac_f32_e32 v132, v31, v31
	v_fmac_f32_e32 v132, v0, v0
	v_fmac_f32_e32 v132, v1, v1
	v_fmac_f32_e32 v132, v2, v2
	v_fmac_f32_e32 v132, v3, v3
	v_fmac_f32_e32 v132, v4, v4
	v_fmac_f32_e32 v132, v5, v5
	v_fmac_f32_e32 v132, v6, v6
	v_fmac_f32_e32 v132, v7, v7
	v_fmac_f32_e32 v132, v8, v8
	v_fmac_f32_e32 v132, v9, v9
	v_fmac_f32_e32 v132, v10, v10
	v_fmac_f32_e32 v132, v11, v11
	v_pk_mul_f32 v[130:131], v[12:13], v[12:13]
	v_pk_mul_f32 v[128:129], v[14:15], v[14:15]
	v_add_f32_e32 v130, v130, v132
	v_add_f32_e32 v130, v131, v130
	v_add_f32_e32 v128, v128, v130
	v_add_f32_e32 v128, v129, v128
	v_xor_b32_e32 v129, 0x80, v214
	ds_bpermute_b32 v129, v129, v128
	s_waitcnt vmcnt(9)
	v_permlane32_swap_b32_e32 v188, v190
	v_permlane32_swap_b32_e32 v189, v191
	s_waitcnt vmcnt(8)
	v_permlane32_swap_b32_e32 v192, v194
	v_permlane32_swap_b32_e32 v193, v195
	s_waitcnt vmcnt(7)
	v_permlane32_swap_b32_e32 v196, v198
	v_permlane32_swap_b32_e32 v197, v199
	s_waitcnt vmcnt(6)
	v_permlane32_swap_b32_e32 v202, v204
	v_permlane32_swap_b32_e32 v203, v205
	v_mov_b64_e32 v[174:175], v[188:189]
	v_mov_b64_e32 v[176:177], v[190:191]
	v_mov_b64_e32 v[178:179], v[192:193]
	v_mov_b64_e32 v[180:181], v[194:195]
	v_mov_b64_e32 v[154:155], v[196:197]
	v_mov_b64_e32 v[152:153], v[198:199]
	v_mov_b64_e32 v[150:151], v[202:203]
	v_mov_b64_e32 v[148:149], v[204:205]
	global_load_dwordx4 v[166:169], v[146:147], off offset:64
	global_load_dwordx4 v[170:173], v[146:147], off offset:96
	global_load_dwordx4 v[140:143], v[146:147], off offset:128
	global_load_dwordx4 v[136:139], v[146:147], off offset:160
	s_add_i32 s16, s16, s48
	s_add_u32 s12, s12, s26
	s_addc_u32 s13, s13, s27
	s_waitcnt lgkmcnt(0)
	v_add_f32_e32 v128, v128, v129
	v_fmamk_f32 v128, v128, 0x3b800000, v228
	v_mul_f32_e32 v129, 0x4f800000, v128
	v_cmp_gt_f32_e32 vcc, s1, v128
	s_cmpk_gt_i32 s16, 0xff
	v_lshlrev_b32_e32 v157, 16, v174
	v_cndmask_b32_e32 v128, v128, v129, vcc
	v_sqrt_f32_e32 v129, v128
	v_and_b32_e32 v174, 0xffff0000, v174
	v_mul_f32_e32 v183, 0xbfb8aa3b, v174
	v_exp_f32_e32 v183, v183
	v_add_u32_e32 v130, -1, v129
	v_fma_f32 v131, -v130, v129, v128
	v_cmp_ge_f32_e64 s[8:9], 0, v131
	v_add_u32_e32 v131, 1, v129
	s_nop 0
	v_cndmask_b32_e64 v130, v129, v130, s[8:9]
	v_fma_f32 v129, -v131, v129, v128
	v_cmp_lt_f32_e64 s[8:9], 0, v129
	s_nop 1
	v_cndmask_b32_e64 v129, v130, v131, s[8:9]
	v_mul_f32_e32 v130, 0x37800000, v129
	v_cndmask_b32_e32 v129, v129, v130, vcc
	v_cmp_class_f32_e32 vcc, v128, v229
	s_nop 1
	v_cndmask_b32_e32 v128, v129, v128, vcc
	v_div_scale_f32 v129, s[8:9], v128, v128, 1.0
	v_rcp_f32_e32 v130, v129
	s_nop 0
	v_fma_f32 v131, -v129, v130, 1.0
	v_fmac_f32_e32 v130, v131, v130
	v_div_scale_f32 v131, vcc, 1.0, v128, 1.0
	v_mul_f32_e32 v132, v131, v130
	v_fma_f32 v133, -v129, v132, v131
	v_fmac_f32_e32 v132, v133, v130
	v_fma_f32 v129, -v129, v132, v131
	v_div_fmas_f32 v129, v129, v130, v132
	v_div_fixup_f32 v156, v129, v128, 1.0
	v_mul_f32_e32 v128, 0xbfb8aa3b, v157
	v_exp_f32_e32 v182, v128
	global_load_dwordx4 v[132:135], v[146:147], off offset:192
	global_load_dwordx4 v[128:131], v[146:147], off offset:224
	v_add_f32_e32 v182, 1.0, v182
	v_rcp_f32_e32 v182, v182
	s_nop 0
	v_mul_f32_e32 v157, v182, v157
	v_mul_f32_e32 v112, v112, v157
	v_add_f32_e32 v157, 1.0, v183
	v_rcp_f32_e32 v157, v157
	v_mul_f32_e32 v112, v156, v112
	v_lshlrev_b32_e32 v182, 16, v175
	v_mul_f32_e32 v183, 0xbfb8aa3b, v182
	s_waitcnt vmcnt(7)
	v_mul_f32_e32 v112, v158, v112
	v_and_b32_e32 v158, 0xffff0000, v175
	v_exp_f32_e32 v183, v183
	v_mul_f32_e32 v157, v157, v174
	v_mul_f32_e32 v174, 0xbfb8aa3b, v158
	v_exp_f32_e32 v174, v174
	v_mul_f32_e32 v113, v113, v157
	v_add_f32_e32 v157, 1.0, v183
	v_mul_f32_e32 v113, v156, v113
	v_rcp_f32_e32 v157, v157
	v_mul_f32_e32 v113, v159, v113
	v_add_f32_e32 v159, 1.0, v174
	v_rcp_f32_e32 v159, v159
	v_mul_f32_e32 v157, v157, v182
	v_mul_f32_e32 v114, v114, v157
	v_mul_f32_e32 v114, v156, v114
	v_mul_f32_e32 v157, v159, v158
	v_mul_f32_e32 v115, v115, v157
	v_lshlrev_b32_e32 v157, 16, v176
	v_mul_f32_e32 v158, 0xbfb8aa3b, v157
	v_exp_f32_e32 v158, v158
	v_mul_f32_e32 v115, v156, v115
	v_mul_f32_e32 v114, v160, v114
	v_mul_f32_e32 v115, v161, v115
	v_cvt_pk_bf16_f32 v112, v112, v113
	v_cvt_pk_bf16_f32 v113, v114, v115
	v_mov_b64_e32 v[238:239], v[112:113]
	v_add_f32_e32 v112, 1.0, v158
	v_and_b32_e32 v113, 0xffff0000, v176
	v_rcp_f32_e32 v112, v112
	v_mul_f32_e32 v114, 0xbfb8aa3b, v113
	v_exp_f32_e32 v114, v114
	v_lshlrev_b32_e32 v115, 16, v177
	v_mul_f32_e32 v112, v112, v157
	v_mul_f32_e32 v112, v116, v112
	v_add_f32_e32 v114, 1.0, v114
	v_mul_f32_e32 v116, 0xbfb8aa3b, v115
	v_rcp_f32_e32 v114, v114
	v_exp_f32_e32 v116, v116
	v_mul_f32_e32 v112, v156, v112
	s_waitcnt vmcnt(6)
	v_mul_f32_e32 v112, v162, v112
	v_mul_f32_e32 v113, v114, v113
	v_add_f32_e32 v114, 1.0, v116
	v_and_b32_e32 v116, 0xffff0000, v177
	v_mul_f32_e32 v113, v117, v113
	v_mul_f32_e32 v117, 0xbfb8aa3b, v116
	v_rcp_f32_e32 v114, v114
	v_exp_f32_e32 v117, v117
	v_mul_f32_e32 v113, v156, v113
	v_mul_f32_e32 v113, v163, v113
	v_mul_f32_e32 v114, v114, v115
	v_add_f32_e32 v115, 1.0, v117
	v_rcp_f32_e32 v115, v115
	v_mul_f32_e32 v114, v118, v114
	v_mul_f32_e32 v114, v156, v114
	v_mul_f32_e32 v114, v164, v114
	v_mul_f32_e32 v115, v115, v116
	v_lshlrev_b32_e32 v116, 16, v178
	v_mul_f32_e32 v117, 0xbfb8aa3b, v116
	v_mul_f32_e32 v115, v119, v115
	v_exp_f32_e32 v117, v117
	v_mul_f32_e32 v115, v156, v115
	v_mul_f32_e32 v115, v165, v115
	v_cvt_pk_bf16_f32 v112, v112, v113
	v_cvt_pk_bf16_f32 v113, v114, v115
	v_mov_b64_e32 v[240:241], v[112:113]
	s_nop 1
	v_permlane32_swap_b32_e32 v238, v240
	v_permlane32_swap_b32_e32 v239, v241
	global_store_dwordx4 v[206:207], v[238:241], off offset:0
	v_and_b32_e32 v113, 0xffff0000, v178
	v_add_f32_e32 v112, 1.0, v117
	v_mul_f32_e32 v114, 0xbfb8aa3b, v113
	v_rcp_f32_e32 v112, v112
	v_exp_f32_e32 v114, v114
	v_lshlrev_b32_e32 v115, 16, v179
	v_mul_f32_e32 v112, v112, v116
	v_add_f32_e32 v114, 1.0, v114
	v_mul_f32_e32 v116, 0xbfb8aa3b, v115
	v_rcp_f32_e32 v114, v114
	v_exp_f32_e32 v116, v116
	v_mul_f32_e32 v112, v120, v112
	v_mul_f32_e32 v112, v156, v112
	v_mul_f32_e32 v113, v114, v113
	v_add_f32_e32 v114, 1.0, v116
	v_and_b32_e32 v116, 0xffff0000, v179
	v_mul_f32_e32 v117, 0xbfb8aa3b, v116
	v_rcp_f32_e32 v114, v114
	v_exp_f32_e32 v117, v117
	v_mul_f32_e32 v113, v121, v113
	v_mul_f32_e32 v113, v156, v113
	v_mul_f32_e32 v114, v114, v115
	v_add_f32_e32 v115, 1.0, v117
	v_rcp_f32_e32 v115, v115
	v_mul_f32_e32 v114, v122, v114
	s_waitcnt vmcnt(6)
	v_mul_f32_e32 v112, v166, v112
	v_mul_f32_e32 v113, v167, v113
	v_mul_f32_e32 v115, v115, v116
	v_lshlrev_b32_e32 v116, 16, v180
	v_mul_f32_e32 v117, 0xbfb8aa3b, v116
	v_mul_f32_e32 v115, v123, v115
	v_exp_f32_e32 v117, v117
	v_mul_f32_e32 v114, v156, v114
	v_mul_f32_e32 v115, v156, v115
	v_mul_f32_e32 v114, v168, v114
	v_mul_f32_e32 v115, v169, v115
	v_cvt_pk_bf16_f32 v112, v112, v113
	v_cvt_pk_bf16_f32 v113, v114, v115
	v_mov_b64_e32 v[242:243], v[112:113]
	v_and_b32_e32 v113, 0xffff0000, v180
	v_add_f32_e32 v112, 1.0, v117
	v_mul_f32_e32 v114, 0xbfb8aa3b, v113
	v_rcp_f32_e32 v112, v112
	v_exp_f32_e32 v114, v114
	v_lshlrev_b32_e32 v115, 16, v181
	v_mul_f32_e32 v112, v112, v116
	v_add_f32_e32 v114, 1.0, v114
	v_mul_f32_e32 v116, 0xbfb8aa3b, v115
	v_rcp_f32_e32 v114, v114
	v_exp_f32_e32 v116, v116
	v_mul_f32_e32 v112, v124, v112
	v_mul_f32_e32 v112, v156, v112
	v_mul_f32_e32 v113, v114, v113
	v_add_f32_e32 v114, 1.0, v116
	v_and_b32_e32 v116, 0xffff0000, v181
	v_mul_f32_e32 v117, 0xbfb8aa3b, v116
	v_rcp_f32_e32 v114, v114
	v_exp_f32_e32 v117, v117
	v_mul_f32_e32 v113, v125, v113
	v_mul_f32_e32 v113, v156, v113
	v_mul_f32_e32 v114, v114, v115
	v_add_f32_e32 v115, 1.0, v117
	v_rcp_f32_e32 v115, v115
	v_mul_f32_e32 v114, v126, v114
	s_waitcnt vmcnt(5)
	v_mul_f32_e32 v112, v170, v112
	v_mul_f32_e32 v113, v171, v113
	v_mul_f32_e32 v115, v115, v116
	v_lshlrev_b32_e32 v116, 16, v154
	v_mul_f32_e32 v117, 0xbfb8aa3b, v116
	v_exp_f32_e32 v117, v117
	v_mul_f32_e32 v115, v127, v115
	v_mul_f32_e32 v114, v156, v114
	v_mul_f32_e32 v115, v156, v115
	v_mul_f32_e32 v114, v172, v114
	v_mul_f32_e32 v115, v173, v115
	v_cvt_pk_bf16_f32 v112, v112, v113
	v_cvt_pk_bf16_f32 v113, v114, v115
	v_mov_b64_e32 v[244:245], v[112:113]
	s_nop 1
	v_permlane32_swap_b32_e32 v242, v244
	v_permlane32_swap_b32_e32 v243, v245
	global_store_dwordx4 v[206:207], v[242:245], off offset:32
	v_add_f32_e32 v112, 1.0, v117
	v_and_b32_e32 v113, 0xffff0000, v154
	v_rcp_f32_e32 v112, v112
	v_mul_f32_e32 v114, 0xbfb8aa3b, v113
	v_exp_f32_e32 v114, v114
	v_mul_f32_e32 v112, v112, v116
	v_mul_f32_e32 v96, v96, v112
	v_add_f32_e32 v112, 1.0, v114
	v_lshlrev_b32_e32 v114, 16, v155
	v_rcp_f32_e32 v112, v112
	v_mul_f32_e32 v115, 0xbfb8aa3b, v114
	v_exp_f32_e32 v115, v115
	v_mul_f32_e32 v96, v156, v96
	v_mul_f32_e32 v112, v112, v113
	v_and_b32_e32 v113, 0xffff0000, v155
	v_mul_f32_e32 v97, v97, v112
	v_add_f32_e32 v112, 1.0, v115
	v_mul_f32_e32 v115, 0xbfb8aa3b, v113
	v_rcp_f32_e32 v112, v112
	v_exp_f32_e32 v115, v115
	v_mul_f32_e32 v97, v156, v97
	s_waitcnt vmcnt(5)
	v_mul_f32_e32 v96, v140, v96
	v_mul_f32_e32 v112, v112, v114
	v_add_f32_e32 v114, 1.0, v115
	v_rcp_f32_e32 v114, v114
	v_mul_f32_e32 v98, v98, v112
	v_mul_f32_e32 v97, v141, v97
	v_mul_f32_e32 v98, v156, v98
	v_mul_f32_e32 v112, v114, v113
	v_mul_f32_e32 v99, v99, v112
	v_lshlrev_b32_e32 v112, 16, v152
	v_mul_f32_e32 v113, 0xbfb8aa3b, v112
	v_exp_f32_e32 v113, v113
	v_mul_f32_e32 v99, v156, v99
	v_mul_f32_e32 v98, v142, v98
	v_mul_f32_e32 v99, v143, v99
	v_cvt_pk_bf16_f32 v96, v96, v97
	v_cvt_pk_bf16_f32 v97, v98, v99
	v_mov_b64_e32 v[246:247], v[96:97]
	v_add_f32_e32 v96, 1.0, v113
	v_and_b32_e32 v97, 0xffff0000, v152
	v_rcp_f32_e32 v96, v96
	v_mul_f32_e32 v98, 0xbfb8aa3b, v97
	v_exp_f32_e32 v98, v98
	v_lshlrev_b32_e32 v99, 16, v153
	v_mul_f32_e32 v96, v96, v112
	v_mul_f32_e32 v96, v100, v96
	v_add_f32_e32 v98, 1.0, v98
	v_mul_f32_e32 v100, 0xbfb8aa3b, v99
	v_rcp_f32_e32 v98, v98
	v_exp_f32_e32 v100, v100
	v_mul_f32_e32 v96, v156, v96
	s_waitcnt vmcnt(4)
	v_mul_f32_e32 v96, v136, v96
	v_mul_f32_e32 v97, v98, v97
	v_add_f32_e32 v98, 1.0, v100
	v_and_b32_e32 v100, 0xffff0000, v153
	v_mul_f32_e32 v97, v101, v97
	v_mul_f32_e32 v101, 0xbfb8aa3b, v100
	v_rcp_f32_e32 v98, v98
	v_exp_f32_e32 v101, v101
	v_mul_f32_e32 v97, v156, v97
	v_mul_f32_e32 v97, v137, v97
	v_mul_f32_e32 v98, v98, v99
	v_add_f32_e32 v99, 1.0, v101
	v_rcp_f32_e32 v99, v99
	v_mul_f32_e32 v98, v102, v98
	v_mul_f32_e32 v98, v156, v98
	v_mul_f32_e32 v98, v138, v98
	v_mul_f32_e32 v99, v99, v100
	v_lshlrev_b32_e32 v100, 16, v150
	v_mul_f32_e32 v101, 0xbfb8aa3b, v100
	v_mul_f32_e32 v99, v103, v99
	v_exp_f32_e32 v101, v101
	v_mul_f32_e32 v99, v156, v99
	v_mul_f32_e32 v99, v139, v99
	v_cvt_pk_bf16_f32 v96, v96, v97
	v_cvt_pk_bf16_f32 v97, v98, v99
	v_mov_b64_e32 v[248:249], v[96:97]
	s_nop 1
	v_permlane32_swap_b32_e32 v246, v248
	v_permlane32_swap_b32_e32 v247, v249
	global_store_dwordx4 v[206:207], v[246:249], off offset:64
	v_and_b32_e32 v97, 0xffff0000, v150
	v_add_f32_e32 v96, 1.0, v101
	v_mul_f32_e32 v98, 0xbfb8aa3b, v97
	v_rcp_f32_e32 v96, v96
	v_exp_f32_e32 v98, v98
	v_lshlrev_b32_e32 v99, 16, v151
	v_mul_f32_e32 v96, v96, v100
	v_add_f32_e32 v98, 1.0, v98
	v_mul_f32_e32 v100, 0xbfb8aa3b, v99
	v_rcp_f32_e32 v98, v98
	v_exp_f32_e32 v100, v100
	v_mul_f32_e32 v96, v104, v96
	v_mul_f32_e32 v96, v156, v96
	v_mul_f32_e32 v97, v98, v97
	v_add_f32_e32 v98, 1.0, v100
	v_and_b32_e32 v100, 0xffff0000, v151
	v_mul_f32_e32 v101, 0xbfb8aa3b, v100
	v_rcp_f32_e32 v98, v98
	v_exp_f32_e32 v101, v101
	v_mul_f32_e32 v97, v105, v97
	v_mul_f32_e32 v97, v156, v97
	v_mul_f32_e32 v98, v98, v99
	v_add_f32_e32 v99, 1.0, v101
	v_rcp_f32_e32 v99, v99
	v_mul_f32_e32 v98, v106, v98
	s_waitcnt vmcnt(4)
	v_mul_f32_e32 v96, v132, v96
	v_mul_f32_e32 v97, v133, v97
	v_mul_f32_e32 v99, v99, v100
	v_lshlrev_b32_e32 v100, 16, v148
	v_mul_f32_e32 v101, 0xbfb8aa3b, v100
	v_mul_f32_e32 v99, v107, v99
	v_exp_f32_e32 v101, v101
	v_mul_f32_e32 v98, v156, v98
	v_mul_f32_e32 v99, v156, v99
	v_mul_f32_e32 v98, v134, v98
	v_mul_f32_e32 v99, v135, v99
	v_cvt_pk_bf16_f32 v96, v96, v97
	v_cvt_pk_bf16_f32 v97, v98, v99
	v_mov_b64_e32 v[230:231], v[96:97]
	v_and_b32_e32 v97, 0xffff0000, v148
	v_add_f32_e32 v96, 1.0, v101
	v_mul_f32_e32 v98, 0xbfb8aa3b, v97
	v_rcp_f32_e32 v96, v96
	v_exp_f32_e32 v98, v98
	v_lshlrev_b32_e32 v99, 16, v149
	v_mul_f32_e32 v96, v96, v100
	v_add_f32_e32 v98, 1.0, v98
	v_mul_f32_e32 v100, 0xbfb8aa3b, v99
	v_rcp_f32_e32 v98, v98
	v_exp_f32_e32 v100, v100
	v_mul_f32_e32 v96, v108, v96
	v_mul_f32_e32 v96, v156, v96
	v_mul_f32_e32 v97, v98, v97
	v_add_f32_e32 v98, 1.0, v100
	v_and_b32_e32 v100, 0xffff0000, v149
	v_mul_f32_e32 v101, 0xbfb8aa3b, v100
	v_rcp_f32_e32 v98, v98
	v_exp_f32_e32 v101, v101
	v_mul_f32_e32 v97, v109, v97
	v_mul_f32_e32 v97, v156, v97
	v_mul_f32_e32 v98, v98, v99
	v_add_f32_e32 v99, 1.0, v101
	v_rcp_f32_e32 v99, v99
	v_mul_f32_e32 v98, v110, v98
	s_waitcnt vmcnt(3)
	v_mul_f32_e32 v96, v128, v96
	v_mul_f32_e32 v97, v129, v97
	v_mul_f32_e32 v99, v99, v100
	v_mul_f32_e32 v99, v111, v99
	v_mul_f32_e32 v98, v156, v98
	v_mul_f32_e32 v99, v156, v99
	v_mul_f32_e32 v98, v130, v98
	v_mul_f32_e32 v99, v131, v99
	v_cvt_pk_bf16_f32 v96, v96, v97
	v_cvt_pk_bf16_f32 v97, v98, v99
	v_permlane32_swap_b32_e32 v210, v212
	v_permlane32_swap_b32_e32 v211, v213
	v_permlane32_swap_b32_e32 v216, v218
	v_permlane32_swap_b32_e32 v217, v219
	v_permlane32_swap_b32_e32 v220, v222
	v_permlane32_swap_b32_e32 v221, v223
	v_permlane32_swap_b32_e32 v224, v226
	v_permlane32_swap_b32_e32 v225, v227
	v_mov_b64_e32 v[136:137], v[210:211]
	v_mov_b64_e32 v[138:139], v[212:213]
	v_mov_b64_e32 v[140:141], v[216:217]
	v_mov_b64_e32 v[142:143], v[218:219]
	v_mov_b64_e32 v[118:119], v[220:221]
	v_mov_b64_e32 v[116:117], v[222:223]
	v_mov_b64_e32 v[114:115], v[224:225]
	v_mov_b64_e32 v[112:113], v[226:227]
	global_load_dwordx4 v[188:191], v[206:207], off offset:256
	global_load_dwordx4 v[192:195], v[206:207], off offset:288
	global_load_dwordx4 v[196:199], v[206:207], off offset:320
	global_load_dwordx4 v[202:205], v[206:207], off offset:352
	v_lshlrev_b32_e32 v148, 16, v136
	v_mov_b64_e32 v[232:233], v[96:97]
	s_nop 1
	v_permlane32_swap_b32_e32 v230, v232
	v_permlane32_swap_b32_e32 v231, v233
	global_store_dwordx4 v[206:207], v[230:233], off offset:96
	global_load_dwordx4 v[120:123], v[146:147], off offset:256
	global_load_dwordx4 v[124:127], v[146:147], off offset:288
	global_load_dwordx4 v[128:131], v[146:147], off offset:320
	global_load_dwordx4 v[132:135], v[146:147], off offset:352
	global_load_dwordx4 v[108:111], v[146:147], off offset:384
	global_load_dwordx4 v[104:107], v[146:147], off offset:416
	v_mul_f32_e32 v96, 0xbfb8aa3b, v148
	v_exp_f32_e32 v149, v96
	v_and_b32_e32 v136, 0xffff0000, v136
	v_mul_f32_e32 v150, 0xbfb8aa3b, v136
	v_exp_f32_e32 v150, v150
	v_add_f32_e32 v149, 1.0, v149
	v_rcp_f32_e32 v149, v149
	global_load_dwordx4 v[100:103], v[146:147], off offset:448
	global_load_dwordx4 v[96:99], v[146:147], off offset:480
	v_mul_f32_e32 v148, v149, v148
	v_mul_f32_e32 v80, v80, v148
	v_add_f32_e32 v148, 1.0, v150
	v_rcp_f32_e32 v148, v148
	v_mul_f32_e32 v80, v156, v80
	v_lshlrev_b32_e32 v149, 16, v137
	v_mul_f32_e32 v150, 0xbfb8aa3b, v149
	v_exp_f32_e32 v150, v150
	s_waitcnt vmcnt(7)
	v_mul_f32_e32 v80, v120, v80
	v_mul_f32_e32 v120, v148, v136
	v_and_b32_e32 v136, 0xffff0000, v137
	v_mul_f32_e32 v137, 0xbfb8aa3b, v136
	v_exp_f32_e32 v137, v137
	v_mul_f32_e32 v81, v81, v120
	v_add_f32_e32 v120, 1.0, v150
	v_mul_f32_e32 v81, v156, v81
	v_rcp_f32_e32 v120, v120
	v_mul_f32_e32 v81, v121, v81
	v_add_f32_e32 v121, 1.0, v137
	v_rcp_f32_e32 v121, v121
	v_mul_f32_e32 v120, v120, v149
	v_mul_f32_e32 v82, v82, v120
	v_mul_f32_e32 v82, v156, v82
	v_mul_f32_e32 v120, v121, v136
	v_mul_f32_e32 v83, v83, v120
	v_lshlrev_b32_e32 v120, 16, v138
	v_mul_f32_e32 v121, 0xbfb8aa3b, v120
	v_exp_f32_e32 v121, v121
	v_mul_f32_e32 v83, v156, v83
	v_mul_f32_e32 v82, v122, v82
	v_mul_f32_e32 v83, v123, v83
	v_cvt_pk_bf16_f32 v80, v80, v81
	v_cvt_pk_bf16_f32 v81, v82, v83
	v_mov_b64_e32 v[238:239], v[80:81]
	v_add_f32_e32 v80, 1.0, v121
	v_and_b32_e32 v81, 0xffff0000, v138
	v_rcp_f32_e32 v80, v80
	v_mul_f32_e32 v82, 0xbfb8aa3b, v81
	v_exp_f32_e32 v82, v82
	v_lshlrev_b32_e32 v83, 16, v139
	v_mul_f32_e32 v80, v80, v120
	v_mul_f32_e32 v80, v84, v80
	v_add_f32_e32 v82, 1.0, v82
	v_mul_f32_e32 v84, 0xbfb8aa3b, v83
	v_rcp_f32_e32 v82, v82
	v_exp_f32_e32 v84, v84
	v_mul_f32_e32 v80, v156, v80
	s_waitcnt vmcnt(6)
	v_mul_f32_e32 v80, v124, v80
	v_mul_f32_e32 v81, v82, v81
	v_add_f32_e32 v82, 1.0, v84
	v_and_b32_e32 v84, 0xffff0000, v139
	v_mul_f32_e32 v81, v85, v81
	v_mul_f32_e32 v85, 0xbfb8aa3b, v84
	v_rcp_f32_e32 v82, v82
	v_exp_f32_e32 v85, v85
	v_mul_f32_e32 v81, v156, v81
	v_mul_f32_e32 v81, v125, v81
	v_mul_f32_e32 v82, v82, v83
	v_add_f32_e32 v83, 1.0, v85
	v_rcp_f32_e32 v83, v83
	v_mul_f32_e32 v82, v86, v82
	v_mul_f32_e32 v82, v156, v82
	v_mul_f32_e32 v82, v126, v82
	v_mul_f32_e32 v83, v83, v84
	v_lshlrev_b32_e32 v84, 16, v140
	v_mul_f32_e32 v85, 0xbfb8aa3b, v84
	v_mul_f32_e32 v83, v87, v83
	v_exp_f32_e32 v85, v85
	v_mul_f32_e32 v83, v156, v83
	v_mul_f32_e32 v83, v127, v83
	v_cvt_pk_bf16_f32 v80, v80, v81
	v_cvt_pk_bf16_f32 v81, v82, v83
	v_mov_b64_e32 v[240:241], v[80:81]
	s_nop 1
	v_permlane32_swap_b32_e32 v238, v240
	v_permlane32_swap_b32_e32 v239, v241
	global_store_dwordx4 v[206:207], v[238:241], off offset:128
	v_and_b32_e32 v81, 0xffff0000, v140
	v_add_f32_e32 v80, 1.0, v85
	v_mul_f32_e32 v82, 0xbfb8aa3b, v81
	v_rcp_f32_e32 v80, v80
	v_exp_f32_e32 v82, v82
	v_lshlrev_b32_e32 v83, 16, v141
	v_mul_f32_e32 v80, v80, v84
	v_add_f32_e32 v82, 1.0, v82
	v_mul_f32_e32 v84, 0xbfb8aa3b, v83
	v_rcp_f32_e32 v82, v82
	v_exp_f32_e32 v84, v84
	v_mul_f32_e32 v80, v88, v80
	v_mul_f32_e32 v80, v156, v80
	v_mul_f32_e32 v81, v82, v81
	v_add_f32_e32 v82, 1.0, v84
	v_and_b32_e32 v84, 0xffff0000, v141
	v_mul_f32_e32 v85, 0xbfb8aa3b, v84
	v_rcp_f32_e32 v82, v82
	v_exp_f32_e32 v85, v85
	v_mul_f32_e32 v81, v89, v81
	v_mul_f32_e32 v81, v156, v81
	v_mul_f32_e32 v82, v82, v83
	v_add_f32_e32 v83, 1.0, v85
	v_rcp_f32_e32 v83, v83
	v_mul_f32_e32 v82, v90, v82
	s_waitcnt vmcnt(6)
	v_mul_f32_e32 v80, v128, v80
	v_mul_f32_e32 v81, v129, v81
	v_mul_f32_e32 v83, v83, v84
	v_lshlrev_b32_e32 v84, 16, v142
	v_mul_f32_e32 v85, 0xbfb8aa3b, v84
	v_mul_f32_e32 v83, v91, v83
	v_exp_f32_e32 v85, v85
	v_mul_f32_e32 v82, v156, v82
	v_mul_f32_e32 v83, v156, v83
	v_mul_f32_e32 v82, v130, v82
	v_mul_f32_e32 v83, v131, v83
	v_cvt_pk_bf16_f32 v80, v80, v81
	v_cvt_pk_bf16_f32 v81, v82, v83
	v_mov_b64_e32 v[242:243], v[80:81]
	v_and_b32_e32 v81, 0xffff0000, v142
	v_add_f32_e32 v80, 1.0, v85
	v_mul_f32_e32 v82, 0xbfb8aa3b, v81
	v_rcp_f32_e32 v80, v80
	v_exp_f32_e32 v82, v82
	v_lshlrev_b32_e32 v83, 16, v143
	v_mul_f32_e32 v80, v80, v84
	v_add_f32_e32 v82, 1.0, v82
	v_mul_f32_e32 v84, 0xbfb8aa3b, v83
	v_rcp_f32_e32 v82, v82
	v_exp_f32_e32 v84, v84
	v_mul_f32_e32 v80, v92, v80
	v_mul_f32_e32 v80, v156, v80
	v_mul_f32_e32 v81, v82, v81
	v_add_f32_e32 v82, 1.0, v84
	v_and_b32_e32 v84, 0xffff0000, v143
	v_mul_f32_e32 v85, 0xbfb8aa3b, v84
	v_rcp_f32_e32 v82, v82
	v_exp_f32_e32 v85, v85
	v_mul_f32_e32 v81, v93, v81
	v_mul_f32_e32 v81, v156, v81
	v_mul_f32_e32 v82, v82, v83
	v_add_f32_e32 v83, 1.0, v85
	v_rcp_f32_e32 v83, v83
	v_mul_f32_e32 v82, v94, v82
	s_waitcnt vmcnt(5)
	v_mul_f32_e32 v80, v132, v80
	v_mul_f32_e32 v81, v133, v81
	v_mul_f32_e32 v83, v83, v84
	v_lshlrev_b32_e32 v84, 16, v118
	v_mul_f32_e32 v85, 0xbfb8aa3b, v84
	v_exp_f32_e32 v85, v85
	v_mul_f32_e32 v83, v95, v83
	v_mul_f32_e32 v82, v156, v82
	v_mul_f32_e32 v83, v156, v83
	v_mul_f32_e32 v82, v134, v82
	v_mul_f32_e32 v83, v135, v83
	v_cvt_pk_bf16_f32 v80, v80, v81
	v_cvt_pk_bf16_f32 v81, v82, v83
	v_mov_b64_e32 v[244:245], v[80:81]
	s_nop 1
	v_permlane32_swap_b32_e32 v242, v244
	v_permlane32_swap_b32_e32 v243, v245
	global_store_dwordx4 v[206:207], v[242:245], off offset:160
	v_add_f32_e32 v80, 1.0, v85
	v_and_b32_e32 v81, 0xffff0000, v118
	v_rcp_f32_e32 v80, v80
	v_mul_f32_e32 v82, 0xbfb8aa3b, v81
	v_exp_f32_e32 v82, v82
	v_mul_f32_e32 v80, v80, v84
	v_mul_f32_e32 v64, v64, v80
	v_add_f32_e32 v80, 1.0, v82
	v_lshlrev_b32_e32 v82, 16, v119
	v_rcp_f32_e32 v80, v80
	v_mul_f32_e32 v83, 0xbfb8aa3b, v82
	v_exp_f32_e32 v83, v83
	v_mul_f32_e32 v64, v156, v64
	v_mul_f32_e32 v80, v80, v81
	v_and_b32_e32 v81, 0xffff0000, v119
	v_mul_f32_e32 v65, v65, v80
	v_add_f32_e32 v80, 1.0, v83
	v_mul_f32_e32 v83, 0xbfb8aa3b, v81
	v_rcp_f32_e32 v80, v80
	v_exp_f32_e32 v83, v83
	v_mul_f32_e32 v65, v156, v65
	s_waitcnt vmcnt(5)
	v_mul_f32_e32 v64, v108, v64
	v_mul_f32_e32 v80, v80, v82
	v_add_f32_e32 v82, 1.0, v83
	v_rcp_f32_e32 v82, v82
	v_mul_f32_e32 v66, v66, v80
	v_mul_f32_e32 v65, v109, v65
	v_mul_f32_e32 v66, v156, v66
	v_mul_f32_e32 v80, v82, v81
	v_mul_f32_e32 v67, v67, v80
	v_lshlrev_b32_e32 v80, 16, v116
	v_mul_f32_e32 v81, 0xbfb8aa3b, v80
	v_exp_f32_e32 v81, v81
	v_mul_f32_e32 v67, v156, v67
	v_mul_f32_e32 v66, v110, v66
	v_mul_f32_e32 v67, v111, v67
	v_cvt_pk_bf16_f32 v64, v64, v65
	v_cvt_pk_bf16_f32 v65, v66, v67
	v_mov_b64_e32 v[246:247], v[64:65]
	v_add_f32_e32 v64, 1.0, v81
	v_and_b32_e32 v65, 0xffff0000, v116
	v_rcp_f32_e32 v64, v64
	v_mul_f32_e32 v66, 0xbfb8aa3b, v65
	v_exp_f32_e32 v66, v66
	v_lshlrev_b32_e32 v67, 16, v117
	v_mul_f32_e32 v64, v64, v80
	v_mul_f32_e32 v64, v68, v64
	v_add_f32_e32 v66, 1.0, v66
	v_mul_f32_e32 v68, 0xbfb8aa3b, v67
	v_rcp_f32_e32 v66, v66
	v_exp_f32_e32 v68, v68
	v_mul_f32_e32 v64, v156, v64
	s_waitcnt vmcnt(4)
	v_mul_f32_e32 v64, v104, v64
	v_mul_f32_e32 v65, v66, v65
	v_add_f32_e32 v66, 1.0, v68
	v_and_b32_e32 v68, 0xffff0000, v117
	v_mul_f32_e32 v65, v69, v65
	v_mul_f32_e32 v69, 0xbfb8aa3b, v68
	v_rcp_f32_e32 v66, v66
	v_exp_f32_e32 v69, v69
	v_mul_f32_e32 v65, v156, v65
	v_mul_f32_e32 v65, v105, v65
	v_mul_f32_e32 v66, v66, v67
	v_add_f32_e32 v67, 1.0, v69
	v_rcp_f32_e32 v67, v67
	v_mul_f32_e32 v66, v70, v66
	v_mul_f32_e32 v66, v156, v66
	v_mul_f32_e32 v66, v106, v66
	v_mul_f32_e32 v67, v67, v68
	v_lshlrev_b32_e32 v68, 16, v114
	v_mul_f32_e32 v69, 0xbfb8aa3b, v68
	v_mul_f32_e32 v67, v71, v67
	v_exp_f32_e32 v69, v69
	v_mul_f32_e32 v67, v156, v67
	v_mul_f32_e32 v67, v107, v67
	v_cvt_pk_bf16_f32 v64, v64, v65
	v_cvt_pk_bf16_f32 v65, v66, v67
	v_mov_b64_e32 v[248:249], v[64:65]
	s_nop 1
	v_permlane32_swap_b32_e32 v246, v248
	v_permlane32_swap_b32_e32 v247, v249
	global_store_dwordx4 v[206:207], v[246:249], off offset:192
	v_and_b32_e32 v65, 0xffff0000, v114
	v_add_f32_e32 v64, 1.0, v69
	v_mul_f32_e32 v66, 0xbfb8aa3b, v65
	v_rcp_f32_e32 v64, v64
	v_exp_f32_e32 v66, v66
	v_lshlrev_b32_e32 v67, 16, v115
	v_mul_f32_e32 v64, v64, v68
	v_add_f32_e32 v66, 1.0, v66
	v_mul_f32_e32 v68, 0xbfb8aa3b, v67
	v_rcp_f32_e32 v66, v66
	v_exp_f32_e32 v68, v68
	v_mul_f32_e32 v64, v72, v64
	v_mul_f32_e32 v64, v156, v64
	v_mul_f32_e32 v65, v66, v65
	v_add_f32_e32 v66, 1.0, v68
	v_and_b32_e32 v68, 0xffff0000, v115
	v_mul_f32_e32 v69, 0xbfb8aa3b, v68
	v_rcp_f32_e32 v66, v66
	v_exp_f32_e32 v69, v69
	v_mul_f32_e32 v65, v73, v65
	v_mul_f32_e32 v65, v156, v65
	v_mul_f32_e32 v66, v66, v67
	v_add_f32_e32 v67, 1.0, v69
	v_rcp_f32_e32 v67, v67
	v_mul_f32_e32 v66, v74, v66
	s_waitcnt vmcnt(4)
	v_mul_f32_e32 v64, v100, v64
	v_mul_f32_e32 v65, v101, v65
	v_mul_f32_e32 v67, v67, v68
	v_lshlrev_b32_e32 v68, 16, v112
	v_mul_f32_e32 v69, 0xbfb8aa3b, v68
	v_mul_f32_e32 v67, v75, v67
	v_exp_f32_e32 v69, v69
	v_mul_f32_e32 v66, v156, v66
	v_mul_f32_e32 v67, v156, v67
	v_mul_f32_e32 v66, v102, v66
	v_mul_f32_e32 v67, v103, v67
	v_cvt_pk_bf16_f32 v64, v64, v65
	v_cvt_pk_bf16_f32 v65, v66, v67
	v_mov_b64_e32 v[230:231], v[64:65]
	v_and_b32_e32 v65, 0xffff0000, v112
	v_add_f32_e32 v64, 1.0, v69
	v_mul_f32_e32 v66, 0xbfb8aa3b, v65
	v_rcp_f32_e32 v64, v64
	v_exp_f32_e32 v66, v66
	v_lshlrev_b32_e32 v67, 16, v113
	v_mul_f32_e32 v64, v64, v68
	v_add_f32_e32 v66, 1.0, v66
	v_mul_f32_e32 v68, 0xbfb8aa3b, v67
	v_rcp_f32_e32 v66, v66
	v_exp_f32_e32 v68, v68
	v_mul_f32_e32 v64, v76, v64
	v_mul_f32_e32 v64, v156, v64
	v_mul_f32_e32 v65, v66, v65
	v_add_f32_e32 v66, 1.0, v68
	v_and_b32_e32 v68, 0xffff0000, v113
	v_mul_f32_e32 v69, 0xbfb8aa3b, v68
	v_rcp_f32_e32 v66, v66
	v_exp_f32_e32 v69, v69
	v_mul_f32_e32 v65, v77, v65
	v_mul_f32_e32 v65, v156, v65
	v_mul_f32_e32 v66, v66, v67
	v_add_f32_e32 v67, 1.0, v69
	v_rcp_f32_e32 v67, v67
	v_mul_f32_e32 v66, v78, v66
	s_waitcnt vmcnt(3)
	v_mul_f32_e32 v64, v96, v64
	v_mul_f32_e32 v65, v97, v65
	v_mul_f32_e32 v67, v67, v68
	v_mul_f32_e32 v67, v79, v67
	v_mul_f32_e32 v66, v156, v66
	v_mul_f32_e32 v67, v156, v67
	v_mul_f32_e32 v66, v98, v66
	v_mul_f32_e32 v67, v99, v67
	v_cvt_pk_bf16_f32 v64, v64, v65
	v_cvt_pk_bf16_f32 v65, v66, v67
	v_permlane32_swap_b32_e32 v188, v190
	v_permlane32_swap_b32_e32 v189, v191
	v_permlane32_swap_b32_e32 v192, v194
	v_permlane32_swap_b32_e32 v193, v195
	v_permlane32_swap_b32_e32 v196, v198
	v_permlane32_swap_b32_e32 v197, v199
	v_permlane32_swap_b32_e32 v202, v204
	v_permlane32_swap_b32_e32 v203, v205
	v_mov_b64_e32 v[104:105], v[188:189]
	v_mov_b64_e32 v[106:107], v[190:191]
	v_mov_b64_e32 v[108:109], v[192:193]
	v_mov_b64_e32 v[110:111], v[194:195]
	v_mov_b64_e32 v[86:87], v[196:197]
	v_mov_b64_e32 v[84:85], v[198:199]
	v_mov_b64_e32 v[82:83], v[202:203]
	v_mov_b64_e32 v[80:81], v[204:205]
	global_load_dwordx4 v[210:213], v[206:207], off offset:384
	global_load_dwordx4 v[216:219], v[206:207], off offset:416
	global_load_dwordx4 v[220:223], v[206:207], off offset:448
	global_load_dwordx4 v[224:227], v[206:207], off offset:480
	v_lshlrev_b32_e32 v112, 16, v104
	v_mov_b64_e32 v[232:233], v[64:65]
	s_nop 1
	v_permlane32_swap_b32_e32 v230, v232
	v_permlane32_swap_b32_e32 v231, v233
	global_store_dwordx4 v[206:207], v[230:233], off offset:224
	global_load_dwordx4 v[88:91], v[146:147], off offset:512
	global_load_dwordx4 v[92:95], v[146:147], off offset:544
	global_load_dwordx4 v[96:99], v[146:147], off offset:576
	global_load_dwordx4 v[100:103], v[146:147], off offset:608
	global_load_dwordx4 v[76:79], v[146:147], off offset:640
	global_load_dwordx4 v[72:75], v[146:147], off offset:672
	v_mul_f32_e32 v64, 0xbfb8aa3b, v112
	v_exp_f32_e32 v113, v64
	v_and_b32_e32 v104, 0xffff0000, v104
	v_mul_f32_e32 v114, 0xbfb8aa3b, v104
	v_exp_f32_e32 v114, v114
	v_add_f32_e32 v113, 1.0, v113
	v_rcp_f32_e32 v113, v113
	global_load_dwordx4 v[68:71], v[146:147], off offset:704
	global_load_dwordx4 v[64:67], v[146:147], off offset:736
	v_mul_f32_e32 v112, v113, v112
	v_mul_f32_e32 v48, v48, v112
	v_add_f32_e32 v112, 1.0, v114
	v_rcp_f32_e32 v112, v112
	v_mul_f32_e32 v48, v156, v48
	v_lshlrev_b32_e32 v113, 16, v105
	v_mul_f32_e32 v114, 0xbfb8aa3b, v113
	v_exp_f32_e32 v114, v114
	s_waitcnt vmcnt(7)
	v_mul_f32_e32 v48, v88, v48
	v_mul_f32_e32 v88, v112, v104
	v_and_b32_e32 v104, 0xffff0000, v105
	v_mul_f32_e32 v105, 0xbfb8aa3b, v104
	v_exp_f32_e32 v105, v105
	v_mul_f32_e32 v49, v49, v88
	v_add_f32_e32 v88, 1.0, v114
	v_mul_f32_e32 v49, v156, v49
	v_rcp_f32_e32 v88, v88
	v_mul_f32_e32 v49, v89, v49
	v_add_f32_e32 v89, 1.0, v105
	v_rcp_f32_e32 v89, v89
	v_mul_f32_e32 v88, v88, v113
	v_mul_f32_e32 v50, v50, v88
	v_mul_f32_e32 v50, v156, v50
	v_mul_f32_e32 v88, v89, v104
	v_mul_f32_e32 v51, v51, v88
	v_lshlrev_b32_e32 v88, 16, v106
	v_mul_f32_e32 v89, 0xbfb8aa3b, v88
	v_exp_f32_e32 v89, v89
	v_mul_f32_e32 v51, v156, v51
	v_mul_f32_e32 v50, v90, v50
	v_mul_f32_e32 v51, v91, v51
	v_cvt_pk_bf16_f32 v48, v48, v49
	v_cvt_pk_bf16_f32 v49, v50, v51
	v_mov_b64_e32 v[238:239], v[48:49]
	v_add_f32_e32 v48, 1.0, v89
	v_and_b32_e32 v49, 0xffff0000, v106
	v_rcp_f32_e32 v48, v48
	v_mul_f32_e32 v50, 0xbfb8aa3b, v49
	v_exp_f32_e32 v50, v50
	v_lshlrev_b32_e32 v51, 16, v107
	v_mul_f32_e32 v48, v48, v88
	v_mul_f32_e32 v48, v52, v48
	v_add_f32_e32 v50, 1.0, v50
	v_mul_f32_e32 v52, 0xbfb8aa3b, v51
	v_rcp_f32_e32 v50, v50
	v_exp_f32_e32 v52, v52
	v_mul_f32_e32 v48, v156, v48
	s_waitcnt vmcnt(6)
	v_mul_f32_e32 v48, v92, v48
	v_mul_f32_e32 v49, v50, v49
	v_add_f32_e32 v50, 1.0, v52
	v_and_b32_e32 v52, 0xffff0000, v107
	v_mul_f32_e32 v49, v53, v49
	v_mul_f32_e32 v53, 0xbfb8aa3b, v52
	v_rcp_f32_e32 v50, v50
	v_exp_f32_e32 v53, v53
	v_mul_f32_e32 v49, v156, v49
	v_mul_f32_e32 v49, v93, v49
	v_mul_f32_e32 v50, v50, v51
	v_add_f32_e32 v51, 1.0, v53
	v_rcp_f32_e32 v51, v51
	v_mul_f32_e32 v50, v54, v50
	v_mul_f32_e32 v50, v156, v50
	v_mul_f32_e32 v50, v94, v50
	v_mul_f32_e32 v51, v51, v52
	v_lshlrev_b32_e32 v52, 16, v108
	v_mul_f32_e32 v53, 0xbfb8aa3b, v52
	v_mul_f32_e32 v51, v55, v51
	v_exp_f32_e32 v53, v53
	v_mul_f32_e32 v51, v156, v51
	v_mul_f32_e32 v51, v95, v51
	v_cvt_pk_bf16_f32 v48, v48, v49
	v_cvt_pk_bf16_f32 v49, v50, v51
	v_mov_b64_e32 v[240:241], v[48:49]
	s_nop 1
	v_permlane32_swap_b32_e32 v238, v240
	v_permlane32_swap_b32_e32 v239, v241
	global_store_dwordx4 v[206:207], v[238:241], off offset:256
	v_and_b32_e32 v49, 0xffff0000, v108
	v_add_f32_e32 v48, 1.0, v53
	v_mul_f32_e32 v50, 0xbfb8aa3b, v49
	v_rcp_f32_e32 v48, v48
	v_exp_f32_e32 v50, v50
	v_lshlrev_b32_e32 v51, 16, v109
	v_mul_f32_e32 v48, v48, v52
	v_add_f32_e32 v50, 1.0, v50
	v_mul_f32_e32 v52, 0xbfb8aa3b, v51
	v_rcp_f32_e32 v50, v50
	v_exp_f32_e32 v52, v52
	v_mul_f32_e32 v48, v56, v48
	v_mul_f32_e32 v48, v156, v48
	v_mul_f32_e32 v49, v50, v49
	v_add_f32_e32 v50, 1.0, v52
	v_and_b32_e32 v52, 0xffff0000, v109
	v_mul_f32_e32 v53, 0xbfb8aa3b, v52
	v_rcp_f32_e32 v50, v50
	v_exp_f32_e32 v53, v53
	v_mul_f32_e32 v49, v57, v49
	v_mul_f32_e32 v49, v156, v49
	v_mul_f32_e32 v50, v50, v51
	v_add_f32_e32 v51, 1.0, v53
	v_rcp_f32_e32 v51, v51
	v_mul_f32_e32 v50, v58, v50
	s_waitcnt vmcnt(6)
	v_mul_f32_e32 v48, v96, v48
	v_mul_f32_e32 v49, v97, v49
	v_mul_f32_e32 v51, v51, v52
	v_lshlrev_b32_e32 v52, 16, v110
	v_mul_f32_e32 v53, 0xbfb8aa3b, v52
	v_mul_f32_e32 v51, v59, v51
	v_exp_f32_e32 v53, v53
	v_mul_f32_e32 v50, v156, v50
	v_mul_f32_e32 v51, v156, v51
	v_mul_f32_e32 v50, v98, v50
	v_mul_f32_e32 v51, v99, v51
	v_cvt_pk_bf16_f32 v48, v48, v49
	v_cvt_pk_bf16_f32 v49, v50, v51
	v_mov_b64_e32 v[242:243], v[48:49]
	v_and_b32_e32 v49, 0xffff0000, v110
	v_add_f32_e32 v48, 1.0, v53
	v_mul_f32_e32 v50, 0xbfb8aa3b, v49
	v_rcp_f32_e32 v48, v48
	v_exp_f32_e32 v50, v50
	v_lshlrev_b32_e32 v51, 16, v111
	v_mul_f32_e32 v48, v48, v52
	v_add_f32_e32 v50, 1.0, v50
	v_mul_f32_e32 v52, 0xbfb8aa3b, v51
	v_rcp_f32_e32 v50, v50
	v_exp_f32_e32 v52, v52
	v_mul_f32_e32 v48, v60, v48
	v_mul_f32_e32 v48, v156, v48
	v_mul_f32_e32 v49, v50, v49
	v_add_f32_e32 v50, 1.0, v52
	v_and_b32_e32 v52, 0xffff0000, v111
	v_mul_f32_e32 v53, 0xbfb8aa3b, v52
	v_rcp_f32_e32 v50, v50
	v_exp_f32_e32 v53, v53
	v_mul_f32_e32 v49, v61, v49
	v_mul_f32_e32 v49, v156, v49
	v_mul_f32_e32 v50, v50, v51
	v_add_f32_e32 v51, 1.0, v53
	v_rcp_f32_e32 v51, v51
	v_mul_f32_e32 v50, v62, v50
	s_waitcnt vmcnt(5)
	v_mul_f32_e32 v48, v100, v48
	v_mul_f32_e32 v49, v101, v49
	v_mul_f32_e32 v51, v51, v52
	v_lshlrev_b32_e32 v52, 16, v86
	v_mul_f32_e32 v53, 0xbfb8aa3b, v52
	v_exp_f32_e32 v53, v53
	v_mul_f32_e32 v51, v63, v51
	v_mul_f32_e32 v50, v156, v50
	v_mul_f32_e32 v51, v156, v51
	v_mul_f32_e32 v50, v102, v50
	v_mul_f32_e32 v51, v103, v51
	v_cvt_pk_bf16_f32 v48, v48, v49
	v_cvt_pk_bf16_f32 v49, v50, v51
	v_mov_b64_e32 v[244:245], v[48:49]
	s_nop 1
	v_permlane32_swap_b32_e32 v242, v244
	v_permlane32_swap_b32_e32 v243, v245
	global_store_dwordx4 v[206:207], v[242:245], off offset:288
	v_add_f32_e32 v48, 1.0, v53
	v_and_b32_e32 v49, 0xffff0000, v86
	v_rcp_f32_e32 v48, v48
	v_mul_f32_e32 v50, 0xbfb8aa3b, v49
	v_exp_f32_e32 v50, v50
	v_mul_f32_e32 v48, v48, v52
	v_mul_f32_e32 v32, v32, v48
	v_add_f32_e32 v48, 1.0, v50
	v_lshlrev_b32_e32 v50, 16, v87
	v_rcp_f32_e32 v48, v48
	v_mul_f32_e32 v51, 0xbfb8aa3b, v50
	v_exp_f32_e32 v51, v51
	v_mul_f32_e32 v32, v156, v32
	v_mul_f32_e32 v48, v48, v49
	v_and_b32_e32 v49, 0xffff0000, v87
	v_mul_f32_e32 v33, v33, v48
	v_add_f32_e32 v48, 1.0, v51
	v_mul_f32_e32 v51, 0xbfb8aa3b, v49
	v_rcp_f32_e32 v48, v48
	v_exp_f32_e32 v51, v51
	v_mul_f32_e32 v33, v156, v33
	s_waitcnt vmcnt(5)
	v_mul_f32_e32 v32, v76, v32
	v_mul_f32_e32 v48, v48, v50
	v_add_f32_e32 v50, 1.0, v51
	v_rcp_f32_e32 v50, v50
	v_mul_f32_e32 v34, v34, v48
	v_mul_f32_e32 v33, v77, v33
	v_mul_f32_e32 v34, v156, v34
	v_mul_f32_e32 v48, v50, v49
	v_mul_f32_e32 v35, v35, v48
	v_lshlrev_b32_e32 v48, 16, v84
	v_mul_f32_e32 v49, 0xbfb8aa3b, v48
	v_exp_f32_e32 v49, v49
	v_mul_f32_e32 v35, v156, v35
	v_mul_f32_e32 v34, v78, v34
	v_mul_f32_e32 v35, v79, v35
	v_cvt_pk_bf16_f32 v32, v32, v33
	v_cvt_pk_bf16_f32 v33, v34, v35
	v_mov_b64_e32 v[246:247], v[32:33]
	v_add_f32_e32 v32, 1.0, v49
	v_and_b32_e32 v33, 0xffff0000, v84
	v_rcp_f32_e32 v32, v32
	v_mul_f32_e32 v34, 0xbfb8aa3b, v33
	v_exp_f32_e32 v34, v34
	v_lshlrev_b32_e32 v35, 16, v85
	v_mul_f32_e32 v32, v32, v48
	v_mul_f32_e32 v32, v36, v32
	v_add_f32_e32 v34, 1.0, v34
	v_mul_f32_e32 v36, 0xbfb8aa3b, v35
	v_rcp_f32_e32 v34, v34
	v_exp_f32_e32 v36, v36
	v_mul_f32_e32 v32, v156, v32
	s_waitcnt vmcnt(4)
	v_mul_f32_e32 v32, v72, v32
	v_mul_f32_e32 v33, v34, v33
	v_add_f32_e32 v34, 1.0, v36
	v_and_b32_e32 v36, 0xffff0000, v85
	v_mul_f32_e32 v33, v37, v33
	v_mul_f32_e32 v37, 0xbfb8aa3b, v36
	v_rcp_f32_e32 v34, v34
	v_exp_f32_e32 v37, v37
	v_mul_f32_e32 v33, v156, v33
	v_mul_f32_e32 v33, v73, v33
	v_mul_f32_e32 v34, v34, v35
	v_add_f32_e32 v35, 1.0, v37
	v_rcp_f32_e32 v35, v35
	v_mul_f32_e32 v34, v38, v34
	v_mul_f32_e32 v34, v156, v34
	v_mul_f32_e32 v34, v74, v34
	v_mul_f32_e32 v35, v35, v36
	v_lshlrev_b32_e32 v36, 16, v82
	v_mul_f32_e32 v37, 0xbfb8aa3b, v36
	v_mul_f32_e32 v35, v39, v35
	v_exp_f32_e32 v37, v37
	v_mul_f32_e32 v35, v156, v35
	v_mul_f32_e32 v35, v75, v35
	v_cvt_pk_bf16_f32 v32, v32, v33
	v_cvt_pk_bf16_f32 v33, v34, v35
	v_mov_b64_e32 v[248:249], v[32:33]
	s_nop 1
	v_permlane32_swap_b32_e32 v246, v248
	v_permlane32_swap_b32_e32 v247, v249
	global_store_dwordx4 v[206:207], v[246:249], off offset:320
	v_and_b32_e32 v33, 0xffff0000, v82
	v_add_f32_e32 v32, 1.0, v37
	v_mul_f32_e32 v34, 0xbfb8aa3b, v33
	v_rcp_f32_e32 v32, v32
	v_exp_f32_e32 v34, v34
	v_lshlrev_b32_e32 v35, 16, v83
	v_mul_f32_e32 v32, v32, v36
	v_add_f32_e32 v34, 1.0, v34
	v_mul_f32_e32 v36, 0xbfb8aa3b, v35
	v_rcp_f32_e32 v34, v34
	v_exp_f32_e32 v36, v36
	v_mul_f32_e32 v32, v40, v32
	v_mul_f32_e32 v32, v156, v32
	v_mul_f32_e32 v33, v34, v33
	v_add_f32_e32 v34, 1.0, v36
	v_and_b32_e32 v36, 0xffff0000, v83
	v_mul_f32_e32 v37, 0xbfb8aa3b, v36
	v_rcp_f32_e32 v34, v34
	v_exp_f32_e32 v37, v37
	v_mul_f32_e32 v33, v41, v33
	v_mul_f32_e32 v33, v156, v33
	v_mul_f32_e32 v34, v34, v35
	v_add_f32_e32 v35, 1.0, v37
	v_rcp_f32_e32 v35, v35
	v_mul_f32_e32 v34, v42, v34
	s_waitcnt vmcnt(4)
	v_mul_f32_e32 v32, v68, v32
	v_mul_f32_e32 v33, v69, v33
	v_mul_f32_e32 v35, v35, v36
	v_lshlrev_b32_e32 v36, 16, v80
	v_mul_f32_e32 v37, 0xbfb8aa3b, v36
	v_mul_f32_e32 v35, v43, v35
	v_exp_f32_e32 v37, v37
	v_mul_f32_e32 v34, v156, v34
	v_mul_f32_e32 v35, v156, v35
	v_mul_f32_e32 v34, v70, v34
	v_mul_f32_e32 v35, v71, v35
	v_cvt_pk_bf16_f32 v32, v32, v33
	v_cvt_pk_bf16_f32 v33, v34, v35
	v_mov_b64_e32 v[230:231], v[32:33]
	v_and_b32_e32 v33, 0xffff0000, v80
	v_add_f32_e32 v32, 1.0, v37
	v_mul_f32_e32 v34, 0xbfb8aa3b, v33
	v_rcp_f32_e32 v32, v32
	v_exp_f32_e32 v34, v34
	v_lshlrev_b32_e32 v35, 16, v81
	v_mul_f32_e32 v32, v32, v36
	v_add_f32_e32 v34, 1.0, v34
	v_mul_f32_e32 v36, 0xbfb8aa3b, v35
	v_rcp_f32_e32 v34, v34
	v_exp_f32_e32 v36, v36
	v_mul_f32_e32 v32, v44, v32
	v_mul_f32_e32 v32, v156, v32
	v_mul_f32_e32 v33, v34, v33
	v_add_f32_e32 v34, 1.0, v36
	v_and_b32_e32 v36, 0xffff0000, v81
	v_mul_f32_e32 v37, 0xbfb8aa3b, v36
	v_rcp_f32_e32 v34, v34
	v_exp_f32_e32 v37, v37
	v_mul_f32_e32 v33, v45, v33
	v_mul_f32_e32 v33, v156, v33
	v_mul_f32_e32 v34, v34, v35
	v_add_f32_e32 v35, 1.0, v37
	v_rcp_f32_e32 v35, v35
	v_mul_f32_e32 v34, v46, v34
	s_waitcnt vmcnt(3)
	v_mul_f32_e32 v32, v64, v32
	v_mul_f32_e32 v33, v65, v33
	v_mul_f32_e32 v35, v35, v36
	v_mul_f32_e32 v35, v47, v35
	v_mul_f32_e32 v34, v156, v34
	v_mul_f32_e32 v35, v156, v35
	v_mul_f32_e32 v34, v66, v34
	v_mul_f32_e32 v35, v67, v35
	v_cvt_pk_bf16_f32 v32, v32, v33
	v_cvt_pk_bf16_f32 v33, v34, v35
	v_permlane32_swap_b32_e32 v210, v212
	v_permlane32_swap_b32_e32 v211, v213
	v_permlane32_swap_b32_e32 v216, v218
	v_permlane32_swap_b32_e32 v217, v219
	v_permlane32_swap_b32_e32 v220, v222
	v_permlane32_swap_b32_e32 v221, v223
	v_permlane32_swap_b32_e32 v224, v226
	v_permlane32_swap_b32_e32 v225, v227
	v_mov_b64_e32 v[72:73], v[210:211]
	v_mov_b64_e32 v[74:75], v[212:213]
	v_mov_b64_e32 v[76:77], v[216:217]
	v_mov_b64_e32 v[78:79], v[218:219]
	v_mov_b64_e32 v[54:55], v[220:221]
	v_mov_b64_e32 v[52:53], v[222:223]
	v_mov_b64_e32 v[50:51], v[224:225]
	v_mov_b64_e32 v[48:49], v[226:227]
	v_lshlrev_b32_e32 v80, 16, v72
	v_mov_b64_e32 v[232:233], v[32:33]
	s_nop 1
	v_permlane32_swap_b32_e32 v230, v232
	v_permlane32_swap_b32_e32 v231, v233
	global_store_dwordx4 v[206:207], v[230:233], off offset:352
	global_load_dwordx4 v[56:59], v[146:147], off offset:768
	global_load_dwordx4 v[60:63], v[146:147], off offset:800
	global_load_dwordx4 v[64:67], v[146:147], off offset:832
	global_load_dwordx4 v[68:71], v[146:147], off offset:864
	global_load_dwordx4 v[44:47], v[146:147], off offset:896
	global_load_dwordx4 v[40:43], v[146:147], off offset:928
	v_mul_f32_e32 v32, 0xbfb8aa3b, v80
	v_exp_f32_e32 v81, v32
	v_and_b32_e32 v72, 0xffff0000, v72
	v_mul_f32_e32 v82, 0xbfb8aa3b, v72
	v_exp_f32_e32 v82, v82
	v_add_f32_e32 v81, 1.0, v81
	v_rcp_f32_e32 v81, v81
	global_load_dwordx4 v[36:39], v[146:147], off offset:960
	global_load_dwordx4 v[32:35], v[146:147], off offset:992
	v_mul_f32_e32 v80, v81, v80
	v_mul_f32_e32 v16, v16, v80
	v_add_f32_e32 v80, 1.0, v82
	v_rcp_f32_e32 v80, v80
	v_mul_f32_e32 v16, v156, v16
	v_lshlrev_b32_e32 v81, 16, v73
	v_mul_f32_e32 v82, 0xbfb8aa3b, v81
	v_exp_f32_e32 v82, v82
	s_waitcnt vmcnt(7)
	v_mul_f32_e32 v16, v56, v16
	v_mul_f32_e32 v56, v80, v72
	v_and_b32_e32 v72, 0xffff0000, v73
	v_mul_f32_e32 v73, 0xbfb8aa3b, v72
	v_exp_f32_e32 v73, v73
	v_mul_f32_e32 v17, v17, v56
	v_add_f32_e32 v56, 1.0, v82
	v_mul_f32_e32 v17, v156, v17
	v_rcp_f32_e32 v56, v56
	v_mul_f32_e32 v17, v57, v17
	v_add_f32_e32 v57, 1.0, v73
	v_rcp_f32_e32 v57, v57
	v_mul_f32_e32 v56, v56, v81
	v_mul_f32_e32 v18, v18, v56
	v_mul_f32_e32 v18, v156, v18
	v_mul_f32_e32 v56, v57, v72
	v_mul_f32_e32 v19, v19, v56
	v_lshlrev_b32_e32 v56, 16, v74
	v_mul_f32_e32 v57, 0xbfb8aa3b, v56
	v_exp_f32_e32 v57, v57
	v_mul_f32_e32 v19, v156, v19
	v_mul_f32_e32 v18, v58, v18
	v_mul_f32_e32 v19, v59, v19
	v_cvt_pk_bf16_f32 v16, v16, v17
	v_cvt_pk_bf16_f32 v17, v18, v19
	v_mov_b64_e32 v[238:239], v[16:17]
	v_add_f32_e32 v16, 1.0, v57
	v_and_b32_e32 v17, 0xffff0000, v74
	v_rcp_f32_e32 v16, v16
	v_mul_f32_e32 v18, 0xbfb8aa3b, v17
	v_exp_f32_e32 v18, v18
	v_lshlrev_b32_e32 v19, 16, v75
	v_mul_f32_e32 v16, v16, v56
	v_mul_f32_e32 v16, v20, v16
	v_add_f32_e32 v18, 1.0, v18
	v_mul_f32_e32 v20, 0xbfb8aa3b, v19
	v_rcp_f32_e32 v18, v18
	v_exp_f32_e32 v20, v20
	v_mul_f32_e32 v16, v156, v16
	s_waitcnt vmcnt(6)
	v_mul_f32_e32 v16, v60, v16
	v_mul_f32_e32 v17, v18, v17
	v_add_f32_e32 v18, 1.0, v20
	v_and_b32_e32 v20, 0xffff0000, v75
	v_mul_f32_e32 v17, v21, v17
	v_mul_f32_e32 v21, 0xbfb8aa3b, v20
	v_rcp_f32_e32 v18, v18
	v_exp_f32_e32 v21, v21
	v_mul_f32_e32 v17, v156, v17
	v_mul_f32_e32 v17, v61, v17
	v_mul_f32_e32 v18, v18, v19
	v_add_f32_e32 v19, 1.0, v21
	v_rcp_f32_e32 v19, v19
	v_mul_f32_e32 v18, v22, v18
	v_mul_f32_e32 v18, v156, v18
	v_mul_f32_e32 v18, v62, v18
	v_mul_f32_e32 v19, v19, v20
	v_lshlrev_b32_e32 v20, 16, v76
	v_mul_f32_e32 v21, 0xbfb8aa3b, v20
	v_mul_f32_e32 v19, v23, v19
	v_exp_f32_e32 v21, v21
	v_mul_f32_e32 v19, v156, v19
	v_mul_f32_e32 v19, v63, v19
	v_cvt_pk_bf16_f32 v16, v16, v17
	v_cvt_pk_bf16_f32 v17, v18, v19
	v_mov_b64_e32 v[240:241], v[16:17]
	s_nop 1
	v_permlane32_swap_b32_e32 v238, v240
	v_permlane32_swap_b32_e32 v239, v241
	global_store_dwordx4 v[206:207], v[238:241], off offset:384
	v_and_b32_e32 v17, 0xffff0000, v76
	v_add_f32_e32 v16, 1.0, v21
	v_mul_f32_e32 v18, 0xbfb8aa3b, v17
	v_rcp_f32_e32 v16, v16
	v_exp_f32_e32 v18, v18
	v_lshlrev_b32_e32 v19, 16, v77
	v_mul_f32_e32 v16, v16, v20
	v_add_f32_e32 v18, 1.0, v18
	v_mul_f32_e32 v20, 0xbfb8aa3b, v19
	v_rcp_f32_e32 v18, v18
	v_exp_f32_e32 v20, v20
	v_mul_f32_e32 v16, v24, v16
	v_mul_f32_e32 v16, v156, v16
	v_mul_f32_e32 v17, v18, v17
	v_add_f32_e32 v18, 1.0, v20
	v_and_b32_e32 v20, 0xffff0000, v77
	v_mul_f32_e32 v21, 0xbfb8aa3b, v20
	v_rcp_f32_e32 v18, v18
	v_exp_f32_e32 v21, v21
	v_mul_f32_e32 v17, v25, v17
	v_mul_f32_e32 v17, v156, v17
	v_mul_f32_e32 v18, v18, v19
	v_add_f32_e32 v19, 1.0, v21
	v_rcp_f32_e32 v19, v19
	v_mul_f32_e32 v18, v26, v18
	s_waitcnt vmcnt(6)
	v_mul_f32_e32 v16, v64, v16
	v_mul_f32_e32 v17, v65, v17
	v_mul_f32_e32 v19, v19, v20
	v_lshlrev_b32_e32 v20, 16, v78
	v_mul_f32_e32 v21, 0xbfb8aa3b, v20
	v_mul_f32_e32 v19, v27, v19
	v_exp_f32_e32 v21, v21
	v_mul_f32_e32 v18, v156, v18
	v_mul_f32_e32 v19, v156, v19
	v_mul_f32_e32 v18, v66, v18
	v_mul_f32_e32 v19, v67, v19
	v_cvt_pk_bf16_f32 v16, v16, v17
	v_cvt_pk_bf16_f32 v17, v18, v19
	v_mov_b64_e32 v[242:243], v[16:17]
	v_and_b32_e32 v17, 0xffff0000, v78
	v_add_f32_e32 v16, 1.0, v21
	v_mul_f32_e32 v18, 0xbfb8aa3b, v17
	v_rcp_f32_e32 v16, v16
	v_exp_f32_e32 v18, v18
	v_lshlrev_b32_e32 v19, 16, v79
	v_mul_f32_e32 v16, v16, v20
	v_add_f32_e32 v18, 1.0, v18
	v_mul_f32_e32 v20, 0xbfb8aa3b, v19
	v_rcp_f32_e32 v18, v18
	v_exp_f32_e32 v20, v20
	v_mul_f32_e32 v16, v28, v16
	v_mul_f32_e32 v16, v156, v16
	v_mul_f32_e32 v17, v18, v17
	v_add_f32_e32 v18, 1.0, v20
	v_and_b32_e32 v20, 0xffff0000, v79
	v_mul_f32_e32 v21, 0xbfb8aa3b, v20
	v_rcp_f32_e32 v18, v18
	v_exp_f32_e32 v21, v21
	v_mul_f32_e32 v17, v29, v17
	v_mul_f32_e32 v17, v156, v17
	v_mul_f32_e32 v18, v18, v19
	v_add_f32_e32 v19, 1.0, v21
	v_rcp_f32_e32 v19, v19
	v_mul_f32_e32 v18, v30, v18
	s_waitcnt vmcnt(5)
	v_mul_f32_e32 v16, v68, v16
	v_mul_f32_e32 v17, v69, v17
	v_mul_f32_e32 v19, v19, v20
	v_lshlrev_b32_e32 v20, 16, v54
	v_mul_f32_e32 v21, 0xbfb8aa3b, v20
	v_exp_f32_e32 v21, v21
	v_mul_f32_e32 v19, v31, v19
	v_mul_f32_e32 v18, v156, v18
	v_mul_f32_e32 v19, v156, v19
	v_mul_f32_e32 v18, v70, v18
	v_mul_f32_e32 v19, v71, v19
	v_cvt_pk_bf16_f32 v16, v16, v17
	v_cvt_pk_bf16_f32 v17, v18, v19
	v_mov_b64_e32 v[244:245], v[16:17]
	s_nop 1
	v_permlane32_swap_b32_e32 v242, v244
	v_permlane32_swap_b32_e32 v243, v245
	global_store_dwordx4 v[206:207], v[242:245], off offset:416
	v_add_f32_e32 v16, 1.0, v21
	v_and_b32_e32 v17, 0xffff0000, v54
	v_rcp_f32_e32 v16, v16
	v_mul_f32_e32 v18, 0xbfb8aa3b, v17
	v_exp_f32_e32 v18, v18
	v_mul_f32_e32 v16, v16, v20
	v_mul_f32_e32 v0, v0, v16
	v_add_f32_e32 v16, 1.0, v18
	v_lshlrev_b32_e32 v18, 16, v55
	v_rcp_f32_e32 v16, v16
	v_mul_f32_e32 v19, 0xbfb8aa3b, v18
	v_exp_f32_e32 v19, v19
	v_mul_f32_e32 v0, v156, v0
	v_mul_f32_e32 v16, v16, v17
	v_and_b32_e32 v17, 0xffff0000, v55
	v_mul_f32_e32 v1, v1, v16
	v_add_f32_e32 v16, 1.0, v19
	v_mul_f32_e32 v19, 0xbfb8aa3b, v17
	v_rcp_f32_e32 v16, v16
	v_exp_f32_e32 v19, v19
	v_mul_f32_e32 v1, v156, v1
	s_waitcnt vmcnt(5)
	v_mul_f32_e32 v0, v44, v0
	v_mul_f32_e32 v16, v16, v18
	v_add_f32_e32 v18, 1.0, v19
	v_rcp_f32_e32 v18, v18
	v_mul_f32_e32 v2, v2, v16
	v_mul_f32_e32 v1, v45, v1
	v_mul_f32_e32 v2, v156, v2
	v_mul_f32_e32 v16, v18, v17
	v_mul_f32_e32 v3, v3, v16
	v_lshlrev_b32_e32 v16, 16, v52
	v_mul_f32_e32 v17, 0xbfb8aa3b, v16
	v_exp_f32_e32 v17, v17
	v_mul_f32_e32 v3, v156, v3
	v_mul_f32_e32 v2, v46, v2
	v_mul_f32_e32 v3, v47, v3
	v_cvt_pk_bf16_f32 v0, v0, v1
	v_cvt_pk_bf16_f32 v1, v2, v3
	v_mov_b64_e32 v[246:247], v[0:1]
	v_add_f32_e32 v0, 1.0, v17
	v_and_b32_e32 v1, 0xffff0000, v52
	v_rcp_f32_e32 v0, v0
	v_mul_f32_e32 v2, 0xbfb8aa3b, v1
	v_exp_f32_e32 v2, v2
	v_lshlrev_b32_e32 v3, 16, v53
	v_mul_f32_e32 v0, v0, v16
	v_mul_f32_e32 v0, v4, v0
	v_add_f32_e32 v2, 1.0, v2
	v_mul_f32_e32 v4, 0xbfb8aa3b, v3
	v_rcp_f32_e32 v2, v2
	v_exp_f32_e32 v4, v4
	v_mul_f32_e32 v0, v156, v0
	s_waitcnt vmcnt(4)
	v_mul_f32_e32 v0, v40, v0
	v_mul_f32_e32 v1, v2, v1
	v_add_f32_e32 v2, 1.0, v4
	v_and_b32_e32 v4, 0xffff0000, v53
	v_mul_f32_e32 v1, v5, v1
	v_mul_f32_e32 v5, 0xbfb8aa3b, v4
	v_rcp_f32_e32 v2, v2
	v_exp_f32_e32 v5, v5
	v_mul_f32_e32 v1, v156, v1
	v_mul_f32_e32 v1, v41, v1
	v_mul_f32_e32 v2, v2, v3
	v_add_f32_e32 v3, 1.0, v5
	v_rcp_f32_e32 v3, v3
	v_mul_f32_e32 v2, v6, v2
	v_mul_f32_e32 v2, v156, v2
	v_mul_f32_e32 v2, v42, v2
	v_mul_f32_e32 v3, v3, v4
	v_lshlrev_b32_e32 v4, 16, v50
	v_mul_f32_e32 v5, 0xbfb8aa3b, v4
	v_mul_f32_e32 v3, v7, v3
	v_exp_f32_e32 v5, v5
	v_mul_f32_e32 v3, v156, v3
	v_mul_f32_e32 v3, v43, v3
	v_cvt_pk_bf16_f32 v0, v0, v1
	v_cvt_pk_bf16_f32 v1, v2, v3
	v_mov_b64_e32 v[248:249], v[0:1]
	s_nop 1
	v_permlane32_swap_b32_e32 v246, v248
	v_permlane32_swap_b32_e32 v247, v249
	global_store_dwordx4 v[206:207], v[246:249], off offset:448
	v_and_b32_e32 v1, 0xffff0000, v50
	v_add_f32_e32 v0, 1.0, v5
	v_mul_f32_e32 v2, 0xbfb8aa3b, v1
	v_rcp_f32_e32 v0, v0
	v_exp_f32_e32 v2, v2
	v_lshlrev_b32_e32 v3, 16, v51
	v_mul_f32_e32 v0, v0, v4
	v_add_f32_e32 v2, 1.0, v2
	v_mul_f32_e32 v4, 0xbfb8aa3b, v3
	v_rcp_f32_e32 v2, v2
	v_exp_f32_e32 v4, v4
	v_mul_f32_e32 v0, v8, v0
	v_mul_f32_e32 v0, v156, v0
	v_mul_f32_e32 v1, v2, v1
	v_add_f32_e32 v2, 1.0, v4
	v_and_b32_e32 v4, 0xffff0000, v51
	v_mul_f32_e32 v5, 0xbfb8aa3b, v4
	v_rcp_f32_e32 v2, v2
	v_exp_f32_e32 v5, v5
	v_mul_f32_e32 v1, v9, v1
	v_mul_f32_e32 v1, v156, v1
	v_mul_f32_e32 v2, v2, v3
	v_add_f32_e32 v3, 1.0, v5
	v_rcp_f32_e32 v3, v3
	v_mul_f32_e32 v2, v10, v2
	s_waitcnt vmcnt(4)
	v_mul_f32_e32 v0, v36, v0
	v_mul_f32_e32 v1, v37, v1
	v_mul_f32_e32 v3, v3, v4
	v_lshlrev_b32_e32 v4, 16, v48
	v_mul_f32_e32 v5, 0xbfb8aa3b, v4
	v_mul_f32_e32 v3, v11, v3
	v_exp_f32_e32 v5, v5
	v_mul_f32_e32 v2, v156, v2
	v_mul_f32_e32 v3, v156, v3
	v_mul_f32_e32 v2, v38, v2
	v_mul_f32_e32 v3, v39, v3
	v_cvt_pk_bf16_f32 v0, v0, v1
	v_cvt_pk_bf16_f32 v1, v2, v3
	v_mov_b64_e32 v[230:231], v[0:1]
	v_and_b32_e32 v1, 0xffff0000, v48
	v_add_f32_e32 v0, 1.0, v5
	v_mul_f32_e32 v2, 0xbfb8aa3b, v1
	v_rcp_f32_e32 v0, v0
	v_exp_f32_e32 v2, v2
	v_lshlrev_b32_e32 v3, 16, v49
	v_mul_f32_e32 v0, v0, v4
	v_add_f32_e32 v2, 1.0, v2
	v_mul_f32_e32 v4, 0xbfb8aa3b, v3
	v_rcp_f32_e32 v2, v2
	v_exp_f32_e32 v4, v4
	v_mul_f32_e32 v0, v12, v0
	v_mul_f32_e32 v0, v156, v0
	v_mul_f32_e32 v1, v2, v1
	v_add_f32_e32 v2, 1.0, v4
	v_and_b32_e32 v4, 0xffff0000, v49
	v_mul_f32_e32 v5, 0xbfb8aa3b, v4
	v_rcp_f32_e32 v2, v2
	v_exp_f32_e32 v5, v5
	v_mul_f32_e32 v1, v13, v1
	v_mul_f32_e32 v1, v156, v1
	v_mul_f32_e32 v2, v2, v3
	v_add_f32_e32 v3, 1.0, v5
	v_rcp_f32_e32 v3, v3
	v_mul_f32_e32 v2, v14, v2
	s_waitcnt vmcnt(3)
	v_mul_f32_e32 v0, v32, v0
	v_mul_f32_e32 v1, v33, v1
	v_mul_f32_e32 v3, v3, v4
	v_mul_f32_e32 v3, v15, v3
	v_mul_f32_e32 v2, v156, v2
	v_mul_f32_e32 v3, v156, v3
	v_mul_f32_e32 v2, v34, v2
	v_mul_f32_e32 v3, v35, v3
	v_cvt_pk_bf16_f32 v0, v0, v1
	v_cvt_pk_bf16_f32 v1, v2, v3
	v_mov_b64_e32 v[232:233], v[0:1]
	s_nop 1
	v_permlane32_swap_b32_e32 v230, v232
	v_permlane32_swap_b32_e32 v231, v233
	global_store_dwordx4 v[206:207], v[230:233], off offset:480
	s_cbranch_scc1 .LBB0_567

.LBB0_686:
	v_mul_f32_e32 v132, v113, v113
	v_fmac_f32_e32 v132, v112, v112
	v_fmac_f32_e32 v132, v114, v114
	v_fmac_f32_e32 v132, v115, v115
	v_fmac_f32_e32 v132, v116, v116
	v_fmac_f32_e32 v132, v117, v117
	v_fmac_f32_e32 v132, v118, v118
	v_fmac_f32_e32 v132, v119, v119
	v_fmac_f32_e32 v132, v120, v120
	v_fmac_f32_e32 v132, v121, v121
	v_fmac_f32_e32 v132, v122, v122
	v_fmac_f32_e32 v132, v123, v123
	v_fmac_f32_e32 v132, v124, v124
	v_fmac_f32_e32 v132, v125, v125
	v_fmac_f32_e32 v132, v126, v126
	v_fmac_f32_e32 v132, v127, v127
	v_fmac_f32_e32 v132, v96, v96
	v_fmac_f32_e32 v132, v97, v97
	v_fmac_f32_e32 v132, v98, v98
	v_fmac_f32_e32 v132, v99, v99
	v_fmac_f32_e32 v132, v100, v100
	v_fmac_f32_e32 v132, v101, v101
	v_fmac_f32_e32 v132, v102, v102
	v_fmac_f32_e32 v132, v103, v103
	v_fmac_f32_e32 v132, v104, v104
	v_fmac_f32_e32 v132, v105, v105
	v_fmac_f32_e32 v132, v106, v106
	v_fmac_f32_e32 v132, v107, v107
	v_fmac_f32_e32 v132, v108, v108
	v_fmac_f32_e32 v132, v109, v109
	v_fmac_f32_e32 v132, v110, v110
	v_fmac_f32_e32 v132, v111, v111
	v_fmac_f32_e32 v132, v80, v80
	v_fmac_f32_e32 v132, v81, v81
	v_fmac_f32_e32 v132, v82, v82
	v_fmac_f32_e32 v132, v83, v83
	v_fmac_f32_e32 v132, v84, v84
	v_fmac_f32_e32 v132, v85, v85
	v_fmac_f32_e32 v132, v86, v86
	v_fmac_f32_e32 v132, v87, v87
	v_fmac_f32_e32 v132, v88, v88
	v_fmac_f32_e32 v132, v89, v89
	v_fmac_f32_e32 v132, v90, v90
	v_fmac_f32_e32 v132, v91, v91
	v_fmac_f32_e32 v132, v92, v92
	v_fmac_f32_e32 v132, v93, v93
	v_fmac_f32_e32 v132, v94, v94
	v_fmac_f32_e32 v132, v95, v95
	v_fmac_f32_e32 v132, v48, v48
	v_fmac_f32_e32 v132, v49, v49
	v_fmac_f32_e32 v132, v50, v50
	v_fmac_f32_e32 v132, v51, v51
	v_fmac_f32_e32 v132, v52, v52
	v_fmac_f32_e32 v132, v53, v53
	v_fmac_f32_e32 v132, v54, v54
	v_fmac_f32_e32 v132, v55, v55
	v_fmac_f32_e32 v132, v56, v56
	v_fmac_f32_e32 v132, v57, v57
	v_fmac_f32_e32 v132, v58, v58
	v_fmac_f32_e32 v132, v59, v59
	v_fmac_f32_e32 v132, v60, v60
	v_fmac_f32_e32 v132, v61, v61
	v_fmac_f32_e32 v132, v62, v62
	v_fmac_f32_e32 v132, v63, v63
	v_fmac_f32_e32 v132, v64, v64
	v_fmac_f32_e32 v132, v65, v65
	v_fmac_f32_e32 v132, v66, v66
	v_fmac_f32_e32 v132, v67, v67
	v_fmac_f32_e32 v132, v68, v68
	v_fmac_f32_e32 v132, v69, v69
	v_fmac_f32_e32 v132, v70, v70
	v_fmac_f32_e32 v132, v71, v71
	v_fmac_f32_e32 v132, v72, v72
	v_fmac_f32_e32 v132, v73, v73
	v_fmac_f32_e32 v132, v74, v74
	v_fmac_f32_e32 v132, v75, v75
	v_lshl_add_u32 v128, s37, 8, v209
	v_fmac_f32_e32 v132, v76, v76
	v_ashrrev_i32_e32 v129, 31, v128
	v_fmac_f32_e32 v132, v77, v77
	v_lshlrev_b64 v[128:129], 12, v[128:129]
	v_fmac_f32_e32 v132, v78, v78
	v_lshl_add_u64 v[128:129], s[4:5], 0, v[128:129]
	s_lshl_b32 s96, s36, 9
	v_fmac_f32_e32 v132, v79, v79
	v_lshl_add_u64 v[128:129], v[128:129], 0, s[96:97]
	s_movk_i32 s8, 0xe0
	v_ashrrev_i32_e32 v209, 31, v208
	v_fmac_f32_e32 v132, v32, v32
	s_load_dwordx2 s[8:9], s[12:13], s8
	s_waitcnt lgkmcnt(0)
	v_lshl_add_u64 v[144:145], v[208:209], 1, v[128:129]
	v_lshl_add_u64 v[206:207], v[208:209], 1, v[144:145]
	v_fmac_f32_e32 v132, v33, v33
	global_load_dwordx4 v[188:191], v[206:207], off offset:0
	global_load_dwordx4 v[192:195], v[206:207], off offset:32
	global_load_dwordx4 v[196:199], v[206:207], off offset:64
	global_load_dwordx4 v[202:205], v[206:207], off offset:96
	global_load_dwordx4 v[210:213], v[206:207], off offset:128
	global_load_dwordx4 v[216:219], v[206:207], off offset:160
	global_load_dwordx4 v[220:223], v[206:207], off offset:192
	global_load_dwordx4 v[224:227], v[206:207], off offset:224
	v_fmac_f32_e32 v132, v34, v34
	v_fmac_f32_e32 v132, v35, v35
	v_fmac_f32_e32 v132, v36, v36
	v_fmac_f32_e32 v132, v37, v37
	v_fmac_f32_e32 v132, v38, v38
	v_fmac_f32_e32 v132, v39, v39
	v_fmac_f32_e32 v132, v40, v40
	v_fmac_f32_e32 v132, v41, v41
	v_fmac_f32_e32 v132, v42, v42
	v_fmac_f32_e32 v132, v43, v43
	v_fmac_f32_e32 v132, v44, v44
	s_add_u32 s8, s8, s18
	v_fmac_f32_e32 v132, v45, v45
	s_addc_u32 s9, s9, s19
	s_lshl_b32 s10, s36, 10
	v_fmac_f32_e32 v132, v46, v46
	s_add_u32 s8, s8, s10
	v_fmac_f32_e32 v132, v47, v47
	s_addc_u32 s9, s9, 0
	v_fmac_f32_e32 v132, v16, v16
	v_lshl_add_u64 v[146:147], v[208:209], 2, s[8:9]
	v_fmac_f32_e32 v132, v17, v17
	global_load_dwordx4 v[158:161], v[146:147], off
	global_load_dwordx4 v[162:165], v[146:147], off offset:32
	v_fmac_f32_e32 v132, v18, v18
	v_fmac_f32_e32 v132, v19, v19
	v_fmac_f32_e32 v132, v20, v20
	v_fmac_f32_e32 v132, v21, v21
	v_fmac_f32_e32 v132, v22, v22
	v_fmac_f32_e32 v132, v23, v23
	v_fmac_f32_e32 v132, v24, v24
	v_fmac_f32_e32 v132, v25, v25
	v_fmac_f32_e32 v132, v26, v26
	v_fmac_f32_e32 v132, v27, v27
	v_fmac_f32_e32 v132, v28, v28
	v_fmac_f32_e32 v132, v29, v29
	v_fmac_f32_e32 v132, v30, v30
	v_fmac_f32_e32 v132, v31, v31
	v_fmac_f32_e32 v132, v0, v0
	v_fmac_f32_e32 v132, v1, v1
	v_fmac_f32_e32 v132, v2, v2
	v_fmac_f32_e32 v132, v3, v3
	v_fmac_f32_e32 v132, v4, v4
	v_fmac_f32_e32 v132, v5, v5
	v_fmac_f32_e32 v132, v6, v6
	v_fmac_f32_e32 v132, v7, v7
	v_fmac_f32_e32 v132, v8, v8
	v_fmac_f32_e32 v132, v9, v9
	v_fmac_f32_e32 v132, v10, v10
	v_fmac_f32_e32 v132, v11, v11
	v_pk_mul_f32 v[130:131], v[12:13], v[12:13]
	v_pk_mul_f32 v[128:129], v[14:15], v[14:15]
	v_add_f32_e32 v130, v130, v132
	v_add_f32_e32 v130, v131, v130
	v_add_f32_e32 v128, v128, v130
	v_add_f32_e32 v128, v129, v128
	v_xor_b32_e32 v129, 0x80, v215
	ds_bpermute_b32 v129, v129, v128
	s_waitcnt vmcnt(9)
	v_permlane32_swap_b32_e32 v188, v190
	v_permlane32_swap_b32_e32 v189, v191
	s_waitcnt vmcnt(8)
	v_permlane32_swap_b32_e32 v192, v194
	v_permlane32_swap_b32_e32 v193, v195
	s_waitcnt vmcnt(7)
	v_permlane32_swap_b32_e32 v196, v198
	v_permlane32_swap_b32_e32 v197, v199
	s_waitcnt vmcnt(6)
	v_permlane32_swap_b32_e32 v202, v204
	v_permlane32_swap_b32_e32 v203, v205
	v_mov_b64_e32 v[174:175], v[188:189]
	v_mov_b64_e32 v[176:177], v[190:191]
	v_mov_b64_e32 v[178:179], v[192:193]
	v_mov_b64_e32 v[180:181], v[194:195]
	v_mov_b64_e32 v[154:155], v[196:197]
	v_mov_b64_e32 v[152:153], v[198:199]
	v_mov_b64_e32 v[150:151], v[202:203]
	v_mov_b64_e32 v[148:149], v[204:205]
	global_load_dwordx4 v[166:169], v[146:147], off offset:64
	global_load_dwordx4 v[170:173], v[146:147], off offset:96
	global_load_dwordx4 v[140:143], v[146:147], off offset:128
	global_load_dwordx4 v[136:139], v[146:147], off offset:160
	s_add_i32 s74, s74, s48
	s_add_i32 s73, s73, s48
	s_cmpk_gt_i32 s74, 0xff
	s_waitcnt lgkmcnt(0)
	v_add_f32_e32 v128, v128, v129
	v_fmamk_f32 v128, v128, 0x3b800000, v228
	v_mul_f32_e32 v129, 0x4f800000, v128
	v_cmp_gt_f32_e32 vcc, s1, v128
	v_lshlrev_b32_e32 v157, 16, v174
	v_cndmask_b32_e32 v128, v128, v129, vcc
	v_sqrt_f32_e32 v129, v128
	v_and_b32_e32 v174, 0xffff0000, v174
	v_mul_f32_e32 v183, 0xbfb8aa3b, v174
	v_exp_f32_e32 v183, v183
	v_add_u32_e32 v130, -1, v129
	v_fma_f32 v131, -v130, v129, v128
	v_cmp_ge_f32_e64 s[8:9], 0, v131
	v_add_u32_e32 v131, 1, v129
	s_nop 0
	v_cndmask_b32_e64 v130, v129, v130, s[8:9]
	v_fma_f32 v129, -v131, v129, v128
	v_cmp_lt_f32_e64 s[8:9], 0, v129
	s_nop 1
	v_cndmask_b32_e64 v129, v130, v131, s[8:9]
	v_mul_f32_e32 v130, 0x37800000, v129
	v_cndmask_b32_e32 v129, v129, v130, vcc
	v_cmp_class_f32_e32 vcc, v128, v229
	s_nop 1
	v_cndmask_b32_e32 v128, v129, v128, vcc
	v_div_scale_f32 v129, s[8:9], v128, v128, 1.0
	v_rcp_f32_e32 v130, v129
	s_nop 0
	v_fma_f32 v131, -v129, v130, 1.0
	v_fmac_f32_e32 v130, v131, v130
	v_div_scale_f32 v131, vcc, 1.0, v128, 1.0
	v_mul_f32_e32 v132, v131, v130
	v_fma_f32 v133, -v129, v132, v131
	v_fmac_f32_e32 v132, v133, v130
	v_fma_f32 v129, -v129, v132, v131
	v_div_fmas_f32 v129, v129, v130, v132
	v_div_fixup_f32 v156, v129, v128, 1.0
	v_mul_f32_e32 v128, 0xbfb8aa3b, v157
	v_exp_f32_e32 v182, v128
	global_load_dwordx4 v[132:135], v[146:147], off offset:192
	global_load_dwordx4 v[128:131], v[146:147], off offset:224
	v_add_f32_e32 v182, 1.0, v182
	v_rcp_f32_e32 v182, v182
	s_nop 0
	v_mul_f32_e32 v157, v182, v157
	v_mul_f32_e32 v112, v112, v157
	v_add_f32_e32 v157, 1.0, v183
	v_rcp_f32_e32 v157, v157
	v_mul_f32_e32 v112, v156, v112
	v_lshlrev_b32_e32 v182, 16, v175
	v_mul_f32_e32 v183, 0xbfb8aa3b, v182
	s_waitcnt vmcnt(7)
	v_mul_f32_e32 v112, v158, v112
	v_and_b32_e32 v158, 0xffff0000, v175
	v_exp_f32_e32 v183, v183
	v_mul_f32_e32 v157, v157, v174
	v_mul_f32_e32 v174, 0xbfb8aa3b, v158
	v_exp_f32_e32 v174, v174
	v_mul_f32_e32 v113, v113, v157
	v_add_f32_e32 v157, 1.0, v183
	v_mul_f32_e32 v113, v156, v113
	v_rcp_f32_e32 v157, v157
	v_mul_f32_e32 v113, v159, v113
	v_add_f32_e32 v159, 1.0, v174
	v_rcp_f32_e32 v159, v159
	v_mul_f32_e32 v157, v157, v182
	v_mul_f32_e32 v114, v114, v157
	v_mul_f32_e32 v114, v156, v114
	v_mul_f32_e32 v157, v159, v158
	v_mul_f32_e32 v115, v115, v157
	v_lshlrev_b32_e32 v157, 16, v176
	v_mul_f32_e32 v158, 0xbfb8aa3b, v157
	v_exp_f32_e32 v158, v158
	v_mul_f32_e32 v115, v156, v115
	v_mul_f32_e32 v114, v160, v114
	v_mul_f32_e32 v115, v161, v115
	v_cvt_pk_bf16_f32 v112, v112, v113
	v_cvt_pk_bf16_f32 v113, v114, v115
	v_mov_b64_e32 v[238:239], v[112:113]
	v_add_f32_e32 v112, 1.0, v158
	v_and_b32_e32 v113, 0xffff0000, v176
	v_rcp_f32_e32 v112, v112
	v_mul_f32_e32 v114, 0xbfb8aa3b, v113
	v_exp_f32_e32 v114, v114
	v_lshlrev_b32_e32 v115, 16, v177
	v_mul_f32_e32 v112, v112, v157
	v_mul_f32_e32 v112, v116, v112
	v_add_f32_e32 v114, 1.0, v114
	v_mul_f32_e32 v116, 0xbfb8aa3b, v115
	v_rcp_f32_e32 v114, v114
	v_exp_f32_e32 v116, v116
	v_mul_f32_e32 v112, v156, v112
	s_waitcnt vmcnt(6)
	v_mul_f32_e32 v112, v162, v112
	v_mul_f32_e32 v113, v114, v113
	v_add_f32_e32 v114, 1.0, v116
	v_and_b32_e32 v116, 0xffff0000, v177
	v_mul_f32_e32 v113, v117, v113
	v_mul_f32_e32 v117, 0xbfb8aa3b, v116
	v_rcp_f32_e32 v114, v114
	v_exp_f32_e32 v117, v117
	v_mul_f32_e32 v113, v156, v113
	v_mul_f32_e32 v113, v163, v113
	v_mul_f32_e32 v114, v114, v115
	v_add_f32_e32 v115, 1.0, v117
	v_rcp_f32_e32 v115, v115
	v_mul_f32_e32 v114, v118, v114
	v_mul_f32_e32 v114, v156, v114
	v_mul_f32_e32 v114, v164, v114
	v_mul_f32_e32 v115, v115, v116
	v_lshlrev_b32_e32 v116, 16, v178
	v_mul_f32_e32 v117, 0xbfb8aa3b, v116
	v_mul_f32_e32 v115, v119, v115
	v_exp_f32_e32 v117, v117
	v_mul_f32_e32 v115, v156, v115
	v_mul_f32_e32 v115, v165, v115
	v_cvt_pk_bf16_f32 v112, v112, v113
	v_cvt_pk_bf16_f32 v113, v114, v115
	v_mov_b64_e32 v[240:241], v[112:113]
	s_nop 1
	v_permlane32_swap_b32_e32 v238, v240
	v_permlane32_swap_b32_e32 v239, v241
	global_store_dwordx4 v[206:207], v[238:241], off offset:0
	v_and_b32_e32 v113, 0xffff0000, v178
	v_add_f32_e32 v112, 1.0, v117
	v_mul_f32_e32 v114, 0xbfb8aa3b, v113
	v_rcp_f32_e32 v112, v112
	v_exp_f32_e32 v114, v114
	v_lshlrev_b32_e32 v115, 16, v179
	v_mul_f32_e32 v112, v112, v116
	v_add_f32_e32 v114, 1.0, v114
	v_mul_f32_e32 v116, 0xbfb8aa3b, v115
	v_rcp_f32_e32 v114, v114
	v_exp_f32_e32 v116, v116
	v_mul_f32_e32 v112, v120, v112
	v_mul_f32_e32 v112, v156, v112
	v_mul_f32_e32 v113, v114, v113
	v_add_f32_e32 v114, 1.0, v116
	v_and_b32_e32 v116, 0xffff0000, v179
	v_mul_f32_e32 v117, 0xbfb8aa3b, v116
	v_rcp_f32_e32 v114, v114
	v_exp_f32_e32 v117, v117
	v_mul_f32_e32 v113, v121, v113
	v_mul_f32_e32 v113, v156, v113
	v_mul_f32_e32 v114, v114, v115
	v_add_f32_e32 v115, 1.0, v117
	v_rcp_f32_e32 v115, v115
	v_mul_f32_e32 v114, v122, v114
	s_waitcnt vmcnt(6)
	v_mul_f32_e32 v112, v166, v112
	v_mul_f32_e32 v113, v167, v113
	v_mul_f32_e32 v115, v115, v116
	v_lshlrev_b32_e32 v116, 16, v180
	v_mul_f32_e32 v117, 0xbfb8aa3b, v116
	v_mul_f32_e32 v115, v123, v115
	v_exp_f32_e32 v117, v117
	v_mul_f32_e32 v114, v156, v114
	v_mul_f32_e32 v115, v156, v115
	v_mul_f32_e32 v114, v168, v114
	v_mul_f32_e32 v115, v169, v115
	v_cvt_pk_bf16_f32 v112, v112, v113
	v_cvt_pk_bf16_f32 v113, v114, v115
	v_mov_b64_e32 v[242:243], v[112:113]
	v_and_b32_e32 v113, 0xffff0000, v180
	v_add_f32_e32 v112, 1.0, v117
	v_mul_f32_e32 v114, 0xbfb8aa3b, v113
	v_rcp_f32_e32 v112, v112
	v_exp_f32_e32 v114, v114
	v_lshlrev_b32_e32 v115, 16, v181
	v_mul_f32_e32 v112, v112, v116
	v_add_f32_e32 v114, 1.0, v114
	v_mul_f32_e32 v116, 0xbfb8aa3b, v115
	v_rcp_f32_e32 v114, v114
	v_exp_f32_e32 v116, v116
	v_mul_f32_e32 v112, v124, v112
	v_mul_f32_e32 v112, v156, v112
	v_mul_f32_e32 v113, v114, v113
	v_add_f32_e32 v114, 1.0, v116
	v_and_b32_e32 v116, 0xffff0000, v181
	v_mul_f32_e32 v117, 0xbfb8aa3b, v116
	v_rcp_f32_e32 v114, v114
	v_exp_f32_e32 v117, v117
	v_mul_f32_e32 v113, v125, v113
	v_mul_f32_e32 v113, v156, v113
	v_mul_f32_e32 v114, v114, v115
	v_add_f32_e32 v115, 1.0, v117
	v_rcp_f32_e32 v115, v115
	v_mul_f32_e32 v114, v126, v114
	s_waitcnt vmcnt(5)
	v_mul_f32_e32 v112, v170, v112
	v_mul_f32_e32 v113, v171, v113
	v_mul_f32_e32 v115, v115, v116
	v_lshlrev_b32_e32 v116, 16, v154
	v_mul_f32_e32 v117, 0xbfb8aa3b, v116
	v_exp_f32_e32 v117, v117
	v_mul_f32_e32 v115, v127, v115
	v_mul_f32_e32 v114, v156, v114
	v_mul_f32_e32 v115, v156, v115
	v_mul_f32_e32 v114, v172, v114
	v_mul_f32_e32 v115, v173, v115
	v_cvt_pk_bf16_f32 v112, v112, v113
	v_cvt_pk_bf16_f32 v113, v114, v115
	v_mov_b64_e32 v[244:245], v[112:113]
	s_nop 1
	v_permlane32_swap_b32_e32 v242, v244
	v_permlane32_swap_b32_e32 v243, v245
	global_store_dwordx4 v[206:207], v[242:245], off offset:32
	v_add_f32_e32 v112, 1.0, v117
	v_and_b32_e32 v113, 0xffff0000, v154
	v_rcp_f32_e32 v112, v112
	v_mul_f32_e32 v114, 0xbfb8aa3b, v113
	v_exp_f32_e32 v114, v114
	v_mul_f32_e32 v112, v112, v116
	v_mul_f32_e32 v96, v96, v112
	v_add_f32_e32 v112, 1.0, v114
	v_lshlrev_b32_e32 v114, 16, v155
	v_rcp_f32_e32 v112, v112
	v_mul_f32_e32 v115, 0xbfb8aa3b, v114
	v_exp_f32_e32 v115, v115
	v_mul_f32_e32 v96, v156, v96
	v_mul_f32_e32 v112, v112, v113
	v_and_b32_e32 v113, 0xffff0000, v155
	v_mul_f32_e32 v97, v97, v112
	v_add_f32_e32 v112, 1.0, v115
	v_mul_f32_e32 v115, 0xbfb8aa3b, v113
	v_rcp_f32_e32 v112, v112
	v_exp_f32_e32 v115, v115
	v_mul_f32_e32 v97, v156, v97
	s_waitcnt vmcnt(5)
	v_mul_f32_e32 v96, v140, v96
	v_mul_f32_e32 v112, v112, v114
	v_add_f32_e32 v114, 1.0, v115
	v_rcp_f32_e32 v114, v114
	v_mul_f32_e32 v98, v98, v112
	v_mul_f32_e32 v97, v141, v97
	v_mul_f32_e32 v98, v156, v98
	v_mul_f32_e32 v112, v114, v113
	v_mul_f32_e32 v99, v99, v112
	v_lshlrev_b32_e32 v112, 16, v152
	v_mul_f32_e32 v113, 0xbfb8aa3b, v112
	v_exp_f32_e32 v113, v113
	v_mul_f32_e32 v99, v156, v99
	v_mul_f32_e32 v98, v142, v98
	v_mul_f32_e32 v99, v143, v99
	v_cvt_pk_bf16_f32 v96, v96, v97
	v_cvt_pk_bf16_f32 v97, v98, v99
	v_mov_b64_e32 v[246:247], v[96:97]
	v_add_f32_e32 v96, 1.0, v113
	v_and_b32_e32 v97, 0xffff0000, v152
	v_rcp_f32_e32 v96, v96
	v_mul_f32_e32 v98, 0xbfb8aa3b, v97
	v_exp_f32_e32 v98, v98
	v_lshlrev_b32_e32 v99, 16, v153
	v_mul_f32_e32 v96, v96, v112
	v_mul_f32_e32 v96, v100, v96
	v_add_f32_e32 v98, 1.0, v98
	v_mul_f32_e32 v100, 0xbfb8aa3b, v99
	v_rcp_f32_e32 v98, v98
	v_exp_f32_e32 v100, v100
	v_mul_f32_e32 v96, v156, v96
	s_waitcnt vmcnt(4)
	v_mul_f32_e32 v96, v136, v96
	v_mul_f32_e32 v97, v98, v97
	v_add_f32_e32 v98, 1.0, v100
	v_and_b32_e32 v100, 0xffff0000, v153
	v_mul_f32_e32 v97, v101, v97
	v_mul_f32_e32 v101, 0xbfb8aa3b, v100
	v_rcp_f32_e32 v98, v98
	v_exp_f32_e32 v101, v101
	v_mul_f32_e32 v97, v156, v97
	v_mul_f32_e32 v97, v137, v97
	v_mul_f32_e32 v98, v98, v99
	v_add_f32_e32 v99, 1.0, v101
	v_rcp_f32_e32 v99, v99
	v_mul_f32_e32 v98, v102, v98
	v_mul_f32_e32 v98, v156, v98
	v_mul_f32_e32 v98, v138, v98
	v_mul_f32_e32 v99, v99, v100
	v_lshlrev_b32_e32 v100, 16, v150
	v_mul_f32_e32 v101, 0xbfb8aa3b, v100
	v_mul_f32_e32 v99, v103, v99
	v_exp_f32_e32 v101, v101
	v_mul_f32_e32 v99, v156, v99
	v_mul_f32_e32 v99, v139, v99
	v_cvt_pk_bf16_f32 v96, v96, v97
	v_cvt_pk_bf16_f32 v97, v98, v99
	v_mov_b64_e32 v[248:249], v[96:97]
	s_nop 1
	v_permlane32_swap_b32_e32 v246, v248
	v_permlane32_swap_b32_e32 v247, v249
	global_store_dwordx4 v[206:207], v[246:249], off offset:64
	v_and_b32_e32 v97, 0xffff0000, v150
	v_add_f32_e32 v96, 1.0, v101
	v_mul_f32_e32 v98, 0xbfb8aa3b, v97
	v_rcp_f32_e32 v96, v96
	v_exp_f32_e32 v98, v98
	v_lshlrev_b32_e32 v99, 16, v151
	v_mul_f32_e32 v96, v96, v100
	v_add_f32_e32 v98, 1.0, v98
	v_mul_f32_e32 v100, 0xbfb8aa3b, v99
	v_rcp_f32_e32 v98, v98
	v_exp_f32_e32 v100, v100
	v_mul_f32_e32 v96, v104, v96
	v_mul_f32_e32 v96, v156, v96
	v_mul_f32_e32 v97, v98, v97
	v_add_f32_e32 v98, 1.0, v100
	v_and_b32_e32 v100, 0xffff0000, v151
	v_mul_f32_e32 v101, 0xbfb8aa3b, v100
	v_rcp_f32_e32 v98, v98
	v_exp_f32_e32 v101, v101
	v_mul_f32_e32 v97, v105, v97
	v_mul_f32_e32 v97, v156, v97
	v_mul_f32_e32 v98, v98, v99
	v_add_f32_e32 v99, 1.0, v101
	v_rcp_f32_e32 v99, v99
	v_mul_f32_e32 v98, v106, v98
	s_waitcnt vmcnt(4)
	v_mul_f32_e32 v96, v132, v96
	v_mul_f32_e32 v97, v133, v97
	v_mul_f32_e32 v99, v99, v100
	v_lshlrev_b32_e32 v100, 16, v148
	v_mul_f32_e32 v101, 0xbfb8aa3b, v100
	v_mul_f32_e32 v99, v107, v99
	v_exp_f32_e32 v101, v101
	v_mul_f32_e32 v98, v156, v98
	v_mul_f32_e32 v99, v156, v99
	v_mul_f32_e32 v98, v134, v98
	v_mul_f32_e32 v99, v135, v99
	v_cvt_pk_bf16_f32 v96, v96, v97
	v_cvt_pk_bf16_f32 v97, v98, v99
	v_mov_b64_e32 v[230:231], v[96:97]
	v_and_b32_e32 v97, 0xffff0000, v148
	v_add_f32_e32 v96, 1.0, v101
	v_mul_f32_e32 v98, 0xbfb8aa3b, v97
	v_rcp_f32_e32 v96, v96
	v_exp_f32_e32 v98, v98
	v_lshlrev_b32_e32 v99, 16, v149
	v_mul_f32_e32 v96, v96, v100
	v_add_f32_e32 v98, 1.0, v98
	v_mul_f32_e32 v100, 0xbfb8aa3b, v99
	v_rcp_f32_e32 v98, v98
	v_exp_f32_e32 v100, v100
	v_mul_f32_e32 v96, v108, v96
	v_mul_f32_e32 v96, v156, v96
	v_mul_f32_e32 v97, v98, v97
	v_add_f32_e32 v98, 1.0, v100
	v_and_b32_e32 v100, 0xffff0000, v149
	v_mul_f32_e32 v101, 0xbfb8aa3b, v100
	v_rcp_f32_e32 v98, v98
	v_exp_f32_e32 v101, v101
	v_mul_f32_e32 v97, v109, v97
	v_mul_f32_e32 v97, v156, v97
	v_mul_f32_e32 v98, v98, v99
	v_add_f32_e32 v99, 1.0, v101
	v_rcp_f32_e32 v99, v99
	v_mul_f32_e32 v98, v110, v98
	s_waitcnt vmcnt(3)
	v_mul_f32_e32 v96, v128, v96
	v_mul_f32_e32 v97, v129, v97
	v_mul_f32_e32 v99, v99, v100
	v_mul_f32_e32 v99, v111, v99
	v_mul_f32_e32 v98, v156, v98
	v_mul_f32_e32 v99, v156, v99
	v_mul_f32_e32 v98, v130, v98
	v_mul_f32_e32 v99, v131, v99
	v_cvt_pk_bf16_f32 v96, v96, v97
	v_cvt_pk_bf16_f32 v97, v98, v99
	v_permlane32_swap_b32_e32 v210, v212
	v_permlane32_swap_b32_e32 v211, v213
	v_permlane32_swap_b32_e32 v216, v218
	v_permlane32_swap_b32_e32 v217, v219
	v_permlane32_swap_b32_e32 v220, v222
	v_permlane32_swap_b32_e32 v221, v223
	v_permlane32_swap_b32_e32 v224, v226
	v_permlane32_swap_b32_e32 v225, v227
	v_mov_b64_e32 v[136:137], v[210:211]
	v_mov_b64_e32 v[138:139], v[212:213]
	v_mov_b64_e32 v[140:141], v[216:217]
	v_mov_b64_e32 v[142:143], v[218:219]
	v_mov_b64_e32 v[118:119], v[220:221]
	v_mov_b64_e32 v[116:117], v[222:223]
	v_mov_b64_e32 v[114:115], v[224:225]
	v_mov_b64_e32 v[112:113], v[226:227]
	global_load_dwordx4 v[188:191], v[206:207], off offset:256
	global_load_dwordx4 v[192:195], v[206:207], off offset:288
	global_load_dwordx4 v[196:199], v[206:207], off offset:320
	global_load_dwordx4 v[202:205], v[206:207], off offset:352
	v_lshlrev_b32_e32 v148, 16, v136
	v_mov_b64_e32 v[232:233], v[96:97]
	s_nop 1
	v_permlane32_swap_b32_e32 v230, v232
	v_permlane32_swap_b32_e32 v231, v233
	global_store_dwordx4 v[206:207], v[230:233], off offset:96
	global_load_dwordx4 v[120:123], v[146:147], off offset:256
	global_load_dwordx4 v[124:127], v[146:147], off offset:288
	global_load_dwordx4 v[128:131], v[146:147], off offset:320
	global_load_dwordx4 v[132:135], v[146:147], off offset:352
	global_load_dwordx4 v[108:111], v[146:147], off offset:384
	global_load_dwordx4 v[104:107], v[146:147], off offset:416
	v_mul_f32_e32 v96, 0xbfb8aa3b, v148
	v_exp_f32_e32 v149, v96
	v_and_b32_e32 v136, 0xffff0000, v136
	v_mul_f32_e32 v150, 0xbfb8aa3b, v136
	v_exp_f32_e32 v150, v150
	v_add_f32_e32 v149, 1.0, v149
	v_rcp_f32_e32 v149, v149
	global_load_dwordx4 v[100:103], v[146:147], off offset:448
	global_load_dwordx4 v[96:99], v[146:147], off offset:480
	v_mul_f32_e32 v148, v149, v148
	v_mul_f32_e32 v80, v80, v148
	v_add_f32_e32 v148, 1.0, v150
	v_rcp_f32_e32 v148, v148
	v_mul_f32_e32 v80, v156, v80
	v_lshlrev_b32_e32 v149, 16, v137
	v_mul_f32_e32 v150, 0xbfb8aa3b, v149
	v_exp_f32_e32 v150, v150
	s_waitcnt vmcnt(7)
	v_mul_f32_e32 v80, v120, v80
	v_mul_f32_e32 v120, v148, v136
	v_and_b32_e32 v136, 0xffff0000, v137
	v_mul_f32_e32 v137, 0xbfb8aa3b, v136
	v_exp_f32_e32 v137, v137
	v_mul_f32_e32 v81, v81, v120
	v_add_f32_e32 v120, 1.0, v150
	v_mul_f32_e32 v81, v156, v81
	v_rcp_f32_e32 v120, v120
	v_mul_f32_e32 v81, v121, v81
	v_add_f32_e32 v121, 1.0, v137
	v_rcp_f32_e32 v121, v121
	v_mul_f32_e32 v120, v120, v149
	v_mul_f32_e32 v82, v82, v120
	v_mul_f32_e32 v82, v156, v82
	v_mul_f32_e32 v120, v121, v136
	v_mul_f32_e32 v83, v83, v120
	v_lshlrev_b32_e32 v120, 16, v138
	v_mul_f32_e32 v121, 0xbfb8aa3b, v120
	v_exp_f32_e32 v121, v121
	v_mul_f32_e32 v83, v156, v83
	v_mul_f32_e32 v82, v122, v82
	v_mul_f32_e32 v83, v123, v83
	v_cvt_pk_bf16_f32 v80, v80, v81
	v_cvt_pk_bf16_f32 v81, v82, v83
	v_mov_b64_e32 v[238:239], v[80:81]
	v_add_f32_e32 v80, 1.0, v121
	v_and_b32_e32 v81, 0xffff0000, v138
	v_rcp_f32_e32 v80, v80
	v_mul_f32_e32 v82, 0xbfb8aa3b, v81
	v_exp_f32_e32 v82, v82
	v_lshlrev_b32_e32 v83, 16, v139
	v_mul_f32_e32 v80, v80, v120
	v_mul_f32_e32 v80, v84, v80
	v_add_f32_e32 v82, 1.0, v82
	v_mul_f32_e32 v84, 0xbfb8aa3b, v83
	v_rcp_f32_e32 v82, v82
	v_exp_f32_e32 v84, v84
	v_mul_f32_e32 v80, v156, v80
	s_waitcnt vmcnt(6)
	v_mul_f32_e32 v80, v124, v80
	v_mul_f32_e32 v81, v82, v81
	v_add_f32_e32 v82, 1.0, v84
	v_and_b32_e32 v84, 0xffff0000, v139
	v_mul_f32_e32 v81, v85, v81
	v_mul_f32_e32 v85, 0xbfb8aa3b, v84
	v_rcp_f32_e32 v82, v82
	v_exp_f32_e32 v85, v85
	v_mul_f32_e32 v81, v156, v81
	v_mul_f32_e32 v81, v125, v81
	v_mul_f32_e32 v82, v82, v83
	v_add_f32_e32 v83, 1.0, v85
	v_rcp_f32_e32 v83, v83
	v_mul_f32_e32 v82, v86, v82
	v_mul_f32_e32 v82, v156, v82
	v_mul_f32_e32 v82, v126, v82
	v_mul_f32_e32 v83, v83, v84
	v_lshlrev_b32_e32 v84, 16, v140
	v_mul_f32_e32 v85, 0xbfb8aa3b, v84
	v_mul_f32_e32 v83, v87, v83
	v_exp_f32_e32 v85, v85
	v_mul_f32_e32 v83, v156, v83
	v_mul_f32_e32 v83, v127, v83
	v_cvt_pk_bf16_f32 v80, v80, v81
	v_cvt_pk_bf16_f32 v81, v82, v83
	v_mov_b64_e32 v[240:241], v[80:81]
	s_nop 1
	v_permlane32_swap_b32_e32 v238, v240
	v_permlane32_swap_b32_e32 v239, v241
	global_store_dwordx4 v[206:207], v[238:241], off offset:128
	v_and_b32_e32 v81, 0xffff0000, v140
	v_add_f32_e32 v80, 1.0, v85
	v_mul_f32_e32 v82, 0xbfb8aa3b, v81
	v_rcp_f32_e32 v80, v80
	v_exp_f32_e32 v82, v82
	v_lshlrev_b32_e32 v83, 16, v141
	v_mul_f32_e32 v80, v80, v84
	v_add_f32_e32 v82, 1.0, v82
	v_mul_f32_e32 v84, 0xbfb8aa3b, v83
	v_rcp_f32_e32 v82, v82
	v_exp_f32_e32 v84, v84
	v_mul_f32_e32 v80, v88, v80
	v_mul_f32_e32 v80, v156, v80
	v_mul_f32_e32 v81, v82, v81
	v_add_f32_e32 v82, 1.0, v84
	v_and_b32_e32 v84, 0xffff0000, v141
	v_mul_f32_e32 v85, 0xbfb8aa3b, v84
	v_rcp_f32_e32 v82, v82
	v_exp_f32_e32 v85, v85
	v_mul_f32_e32 v81, v89, v81
	v_mul_f32_e32 v81, v156, v81
	v_mul_f32_e32 v82, v82, v83
	v_add_f32_e32 v83, 1.0, v85
	v_rcp_f32_e32 v83, v83
	v_mul_f32_e32 v82, v90, v82
	s_waitcnt vmcnt(6)
	v_mul_f32_e32 v80, v128, v80
	v_mul_f32_e32 v81, v129, v81
	v_mul_f32_e32 v83, v83, v84
	v_lshlrev_b32_e32 v84, 16, v142
	v_mul_f32_e32 v85, 0xbfb8aa3b, v84
	v_mul_f32_e32 v83, v91, v83
	v_exp_f32_e32 v85, v85
	v_mul_f32_e32 v82, v156, v82
	v_mul_f32_e32 v83, v156, v83
	v_mul_f32_e32 v82, v130, v82
	v_mul_f32_e32 v83, v131, v83
	v_cvt_pk_bf16_f32 v80, v80, v81
	v_cvt_pk_bf16_f32 v81, v82, v83
	v_mov_b64_e32 v[242:243], v[80:81]
	v_and_b32_e32 v81, 0xffff0000, v142
	v_add_f32_e32 v80, 1.0, v85
	v_mul_f32_e32 v82, 0xbfb8aa3b, v81
	v_rcp_f32_e32 v80, v80
	v_exp_f32_e32 v82, v82
	v_lshlrev_b32_e32 v83, 16, v143
	v_mul_f32_e32 v80, v80, v84
	v_add_f32_e32 v82, 1.0, v82
	v_mul_f32_e32 v84, 0xbfb8aa3b, v83
	v_rcp_f32_e32 v82, v82
	v_exp_f32_e32 v84, v84
	v_mul_f32_e32 v80, v92, v80
	v_mul_f32_e32 v80, v156, v80
	v_mul_f32_e32 v81, v82, v81
	v_add_f32_e32 v82, 1.0, v84
	v_and_b32_e32 v84, 0xffff0000, v143
	v_mul_f32_e32 v85, 0xbfb8aa3b, v84
	v_rcp_f32_e32 v82, v82
	v_exp_f32_e32 v85, v85
	v_mul_f32_e32 v81, v93, v81
	v_mul_f32_e32 v81, v156, v81
	v_mul_f32_e32 v82, v82, v83
	v_add_f32_e32 v83, 1.0, v85
	v_rcp_f32_e32 v83, v83
	v_mul_f32_e32 v82, v94, v82
	s_waitcnt vmcnt(5)
	v_mul_f32_e32 v80, v132, v80
	v_mul_f32_e32 v81, v133, v81
	v_mul_f32_e32 v83, v83, v84
	v_lshlrev_b32_e32 v84, 16, v118
	v_mul_f32_e32 v85, 0xbfb8aa3b, v84
	v_exp_f32_e32 v85, v85
	v_mul_f32_e32 v83, v95, v83
	v_mul_f32_e32 v82, v156, v82
	v_mul_f32_e32 v83, v156, v83
	v_mul_f32_e32 v82, v134, v82
	v_mul_f32_e32 v83, v135, v83
	v_cvt_pk_bf16_f32 v80, v80, v81
	v_cvt_pk_bf16_f32 v81, v82, v83
	v_mov_b64_e32 v[244:245], v[80:81]
	s_nop 1
	v_permlane32_swap_b32_e32 v242, v244
	v_permlane32_swap_b32_e32 v243, v245
	global_store_dwordx4 v[206:207], v[242:245], off offset:160
	v_add_f32_e32 v80, 1.0, v85
	v_and_b32_e32 v81, 0xffff0000, v118
	v_rcp_f32_e32 v80, v80
	v_mul_f32_e32 v82, 0xbfb8aa3b, v81
	v_exp_f32_e32 v82, v82
	v_mul_f32_e32 v80, v80, v84
	v_mul_f32_e32 v48, v48, v80
	v_add_f32_e32 v80, 1.0, v82
	v_lshlrev_b32_e32 v82, 16, v119
	v_rcp_f32_e32 v80, v80
	v_mul_f32_e32 v83, 0xbfb8aa3b, v82
	v_exp_f32_e32 v83, v83
	v_mul_f32_e32 v48, v156, v48
	v_mul_f32_e32 v80, v80, v81
	v_and_b32_e32 v81, 0xffff0000, v119
	v_mul_f32_e32 v49, v49, v80
	v_add_f32_e32 v80, 1.0, v83
	v_mul_f32_e32 v83, 0xbfb8aa3b, v81
	v_rcp_f32_e32 v80, v80
	v_exp_f32_e32 v83, v83
	v_mul_f32_e32 v49, v156, v49
	s_waitcnt vmcnt(5)
	v_mul_f32_e32 v48, v108, v48
	v_mul_f32_e32 v80, v80, v82
	v_add_f32_e32 v82, 1.0, v83
	v_rcp_f32_e32 v82, v82
	v_mul_f32_e32 v50, v50, v80
	v_mul_f32_e32 v49, v109, v49
	v_mul_f32_e32 v50, v156, v50
	v_mul_f32_e32 v80, v82, v81
	v_mul_f32_e32 v51, v51, v80
	v_lshlrev_b32_e32 v80, 16, v116
	v_mul_f32_e32 v81, 0xbfb8aa3b, v80
	v_exp_f32_e32 v81, v81
	v_mul_f32_e32 v51, v156, v51
	v_mul_f32_e32 v50, v110, v50
	v_mul_f32_e32 v51, v111, v51
	v_cvt_pk_bf16_f32 v48, v48, v49
	v_cvt_pk_bf16_f32 v49, v50, v51
	v_mov_b64_e32 v[246:247], v[48:49]
	v_add_f32_e32 v48, 1.0, v81
	v_and_b32_e32 v49, 0xffff0000, v116
	v_rcp_f32_e32 v48, v48
	v_mul_f32_e32 v50, 0xbfb8aa3b, v49
	v_exp_f32_e32 v50, v50
	v_lshlrev_b32_e32 v51, 16, v117
	v_mul_f32_e32 v48, v48, v80
	v_mul_f32_e32 v48, v52, v48
	v_add_f32_e32 v50, 1.0, v50
	v_mul_f32_e32 v52, 0xbfb8aa3b, v51
	v_rcp_f32_e32 v50, v50
	v_exp_f32_e32 v52, v52
	v_mul_f32_e32 v48, v156, v48
	s_waitcnt vmcnt(4)
	v_mul_f32_e32 v48, v104, v48
	v_mul_f32_e32 v49, v50, v49
	v_add_f32_e32 v50, 1.0, v52
	v_and_b32_e32 v52, 0xffff0000, v117
	v_mul_f32_e32 v49, v53, v49
	v_mul_f32_e32 v53, 0xbfb8aa3b, v52
	v_rcp_f32_e32 v50, v50
	v_exp_f32_e32 v53, v53
	v_mul_f32_e32 v49, v156, v49
	v_mul_f32_e32 v49, v105, v49
	v_mul_f32_e32 v50, v50, v51
	v_add_f32_e32 v51, 1.0, v53
	v_rcp_f32_e32 v51, v51
	v_mul_f32_e32 v50, v54, v50
	v_mul_f32_e32 v50, v156, v50
	v_mul_f32_e32 v50, v106, v50
	v_mul_f32_e32 v51, v51, v52
	v_lshlrev_b32_e32 v52, 16, v114
	v_mul_f32_e32 v53, 0xbfb8aa3b, v52
	v_mul_f32_e32 v51, v55, v51
	v_exp_f32_e32 v53, v53
	v_mul_f32_e32 v51, v156, v51
	v_mul_f32_e32 v51, v107, v51
	v_cvt_pk_bf16_f32 v48, v48, v49
	v_cvt_pk_bf16_f32 v49, v50, v51
	v_mov_b64_e32 v[248:249], v[48:49]
	s_nop 1
	v_permlane32_swap_b32_e32 v246, v248
	v_permlane32_swap_b32_e32 v247, v249
	global_store_dwordx4 v[206:207], v[246:249], off offset:192
	v_and_b32_e32 v49, 0xffff0000, v114
	v_add_f32_e32 v48, 1.0, v53
	v_mul_f32_e32 v50, 0xbfb8aa3b, v49
	v_rcp_f32_e32 v48, v48
	v_exp_f32_e32 v50, v50
	v_lshlrev_b32_e32 v51, 16, v115
	v_mul_f32_e32 v48, v48, v52
	v_add_f32_e32 v50, 1.0, v50
	v_mul_f32_e32 v52, 0xbfb8aa3b, v51
	v_rcp_f32_e32 v50, v50
	v_exp_f32_e32 v52, v52
	v_mul_f32_e32 v48, v56, v48
	v_mul_f32_e32 v48, v156, v48
	v_mul_f32_e32 v49, v50, v49
	v_add_f32_e32 v50, 1.0, v52
	v_and_b32_e32 v52, 0xffff0000, v115
	v_mul_f32_e32 v53, 0xbfb8aa3b, v52
	v_rcp_f32_e32 v50, v50
	v_exp_f32_e32 v53, v53
	v_mul_f32_e32 v49, v57, v49
	v_mul_f32_e32 v49, v156, v49
	v_mul_f32_e32 v50, v50, v51
	v_add_f32_e32 v51, 1.0, v53
	v_rcp_f32_e32 v51, v51
	v_mul_f32_e32 v50, v58, v50
	s_waitcnt vmcnt(4)
	v_mul_f32_e32 v48, v100, v48
	v_mul_f32_e32 v49, v101, v49
	v_mul_f32_e32 v51, v51, v52
	v_lshlrev_b32_e32 v52, 16, v112
	v_mul_f32_e32 v53, 0xbfb8aa3b, v52
	v_mul_f32_e32 v51, v59, v51
	v_exp_f32_e32 v53, v53
	v_mul_f32_e32 v50, v156, v50
	v_mul_f32_e32 v51, v156, v51
	v_mul_f32_e32 v50, v102, v50
	v_mul_f32_e32 v51, v103, v51
	v_cvt_pk_bf16_f32 v48, v48, v49
	v_cvt_pk_bf16_f32 v49, v50, v51
	v_mov_b64_e32 v[230:231], v[48:49]
	v_and_b32_e32 v49, 0xffff0000, v112
	v_add_f32_e32 v48, 1.0, v53
	v_mul_f32_e32 v50, 0xbfb8aa3b, v49
	v_rcp_f32_e32 v48, v48
	v_exp_f32_e32 v50, v50
	v_lshlrev_b32_e32 v51, 16, v113
	v_mul_f32_e32 v48, v48, v52
	v_add_f32_e32 v50, 1.0, v50
	v_mul_f32_e32 v52, 0xbfb8aa3b, v51
	v_rcp_f32_e32 v50, v50
	v_exp_f32_e32 v52, v52
	v_mul_f32_e32 v48, v60, v48
	v_mul_f32_e32 v48, v156, v48
	v_mul_f32_e32 v49, v50, v49
	v_add_f32_e32 v50, 1.0, v52
	v_and_b32_e32 v52, 0xffff0000, v113
	v_mul_f32_e32 v53, 0xbfb8aa3b, v52
	v_rcp_f32_e32 v50, v50
	v_exp_f32_e32 v53, v53
	v_mul_f32_e32 v49, v61, v49
	v_mul_f32_e32 v49, v156, v49
	v_mul_f32_e32 v50, v50, v51
	v_add_f32_e32 v51, 1.0, v53
	v_rcp_f32_e32 v51, v51
	v_mul_f32_e32 v50, v62, v50
	s_waitcnt vmcnt(3)
	v_mul_f32_e32 v48, v96, v48
	v_mul_f32_e32 v49, v97, v49
	v_mul_f32_e32 v51, v51, v52
	v_mul_f32_e32 v51, v63, v51
	v_mul_f32_e32 v50, v156, v50
	v_mul_f32_e32 v51, v156, v51
	v_mul_f32_e32 v50, v98, v50
	v_mul_f32_e32 v51, v99, v51
	v_cvt_pk_bf16_f32 v48, v48, v49
	v_cvt_pk_bf16_f32 v49, v50, v51
	v_permlane32_swap_b32_e32 v188, v190
	v_permlane32_swap_b32_e32 v189, v191
	v_permlane32_swap_b32_e32 v192, v194
	v_permlane32_swap_b32_e32 v193, v195
	v_permlane32_swap_b32_e32 v196, v198
	v_permlane32_swap_b32_e32 v197, v199
	v_permlane32_swap_b32_e32 v202, v204
	v_permlane32_swap_b32_e32 v203, v205
	v_mov_b64_e32 v[104:105], v[188:189]
	v_mov_b64_e32 v[106:107], v[190:191]
	v_mov_b64_e32 v[108:109], v[192:193]
	v_mov_b64_e32 v[110:111], v[194:195]
	v_mov_b64_e32 v[86:87], v[196:197]
	v_mov_b64_e32 v[84:85], v[198:199]
	v_mov_b64_e32 v[82:83], v[202:203]
	v_mov_b64_e32 v[80:81], v[204:205]
	global_load_dwordx4 v[210:213], v[206:207], off offset:384
	global_load_dwordx4 v[216:219], v[206:207], off offset:416
	global_load_dwordx4 v[220:223], v[206:207], off offset:448
	global_load_dwordx4 v[224:227], v[206:207], off offset:480
	v_lshlrev_b32_e32 v112, 16, v104
	v_mov_b64_e32 v[232:233], v[48:49]
	s_nop 1
	v_permlane32_swap_b32_e32 v230, v232
	v_permlane32_swap_b32_e32 v231, v233
	global_store_dwordx4 v[206:207], v[230:233], off offset:224
	global_load_dwordx4 v[88:91], v[146:147], off offset:512
	global_load_dwordx4 v[92:95], v[146:147], off offset:544
	global_load_dwordx4 v[96:99], v[146:147], off offset:576
	global_load_dwordx4 v[100:103], v[146:147], off offset:608
	global_load_dwordx4 v[60:63], v[146:147], off offset:640
	global_load_dwordx4 v[56:59], v[146:147], off offset:672
	v_mul_f32_e32 v48, 0xbfb8aa3b, v112
	v_exp_f32_e32 v113, v48
	v_and_b32_e32 v104, 0xffff0000, v104
	v_mul_f32_e32 v114, 0xbfb8aa3b, v104
	v_exp_f32_e32 v114, v114
	v_add_f32_e32 v113, 1.0, v113
	v_rcp_f32_e32 v113, v113
	global_load_dwordx4 v[52:55], v[146:147], off offset:704
	global_load_dwordx4 v[48:51], v[146:147], off offset:736
	v_mul_f32_e32 v112, v113, v112
	v_mul_f32_e32 v64, v64, v112
	v_add_f32_e32 v112, 1.0, v114
	v_rcp_f32_e32 v112, v112
	v_mul_f32_e32 v64, v156, v64
	v_lshlrev_b32_e32 v113, 16, v105
	v_mul_f32_e32 v114, 0xbfb8aa3b, v113
	v_exp_f32_e32 v114, v114
	s_waitcnt vmcnt(7)
	v_mul_f32_e32 v64, v88, v64
	v_mul_f32_e32 v88, v112, v104
	v_and_b32_e32 v104, 0xffff0000, v105
	v_mul_f32_e32 v105, 0xbfb8aa3b, v104
	v_exp_f32_e32 v105, v105
	v_mul_f32_e32 v65, v65, v88
	v_add_f32_e32 v88, 1.0, v114
	v_mul_f32_e32 v65, v156, v65
	v_rcp_f32_e32 v88, v88
	v_mul_f32_e32 v65, v89, v65
	v_add_f32_e32 v89, 1.0, v105
	v_rcp_f32_e32 v89, v89
	v_mul_f32_e32 v88, v88, v113
	v_mul_f32_e32 v66, v66, v88
	v_mul_f32_e32 v66, v156, v66
	v_mul_f32_e32 v88, v89, v104
	v_mul_f32_e32 v67, v67, v88
	v_lshlrev_b32_e32 v88, 16, v106
	v_mul_f32_e32 v89, 0xbfb8aa3b, v88
	v_exp_f32_e32 v89, v89
	v_mul_f32_e32 v67, v156, v67
	v_mul_f32_e32 v66, v90, v66
	v_mul_f32_e32 v67, v91, v67
	v_cvt_pk_bf16_f32 v64, v64, v65
	v_cvt_pk_bf16_f32 v65, v66, v67
	v_mov_b64_e32 v[238:239], v[64:65]
	v_add_f32_e32 v64, 1.0, v89
	v_and_b32_e32 v65, 0xffff0000, v106
	v_rcp_f32_e32 v64, v64
	v_mul_f32_e32 v66, 0xbfb8aa3b, v65
	v_exp_f32_e32 v66, v66
	v_lshlrev_b32_e32 v67, 16, v107
	v_mul_f32_e32 v64, v64, v88
	v_mul_f32_e32 v64, v68, v64
	v_add_f32_e32 v66, 1.0, v66
	v_mul_f32_e32 v68, 0xbfb8aa3b, v67
	v_rcp_f32_e32 v66, v66
	v_exp_f32_e32 v68, v68
	v_mul_f32_e32 v64, v156, v64
	s_waitcnt vmcnt(6)
	v_mul_f32_e32 v64, v92, v64
	v_mul_f32_e32 v65, v66, v65
	v_add_f32_e32 v66, 1.0, v68
	v_and_b32_e32 v68, 0xffff0000, v107
	v_mul_f32_e32 v65, v69, v65
	v_mul_f32_e32 v69, 0xbfb8aa3b, v68
	v_rcp_f32_e32 v66, v66
	v_exp_f32_e32 v69, v69
	v_mul_f32_e32 v65, v156, v65
	v_mul_f32_e32 v65, v93, v65
	v_mul_f32_e32 v66, v66, v67
	v_add_f32_e32 v67, 1.0, v69
	v_rcp_f32_e32 v67, v67
	v_mul_f32_e32 v66, v70, v66
	v_mul_f32_e32 v66, v156, v66
	v_mul_f32_e32 v66, v94, v66
	v_mul_f32_e32 v67, v67, v68
	v_lshlrev_b32_e32 v68, 16, v108
	v_mul_f32_e32 v69, 0xbfb8aa3b, v68
	v_mul_f32_e32 v67, v71, v67
	v_exp_f32_e32 v69, v69
	v_mul_f32_e32 v67, v156, v67
	v_mul_f32_e32 v67, v95, v67
	v_cvt_pk_bf16_f32 v64, v64, v65
	v_cvt_pk_bf16_f32 v65, v66, v67
	v_mov_b64_e32 v[240:241], v[64:65]
	s_nop 1
	v_permlane32_swap_b32_e32 v238, v240
	v_permlane32_swap_b32_e32 v239, v241
	global_store_dwordx4 v[206:207], v[238:241], off offset:256
	v_and_b32_e32 v65, 0xffff0000, v108
	v_add_f32_e32 v64, 1.0, v69
	v_mul_f32_e32 v66, 0xbfb8aa3b, v65
	v_rcp_f32_e32 v64, v64
	v_exp_f32_e32 v66, v66
	v_lshlrev_b32_e32 v67, 16, v109
	v_mul_f32_e32 v64, v64, v68
	v_add_f32_e32 v66, 1.0, v66
	v_mul_f32_e32 v68, 0xbfb8aa3b, v67
	v_rcp_f32_e32 v66, v66
	v_exp_f32_e32 v68, v68
	v_mul_f32_e32 v64, v72, v64
	v_mul_f32_e32 v64, v156, v64
	v_mul_f32_e32 v65, v66, v65
	v_add_f32_e32 v66, 1.0, v68
	v_and_b32_e32 v68, 0xffff0000, v109
	v_mul_f32_e32 v69, 0xbfb8aa3b, v68
	v_rcp_f32_e32 v66, v66
	v_exp_f32_e32 v69, v69
	v_mul_f32_e32 v65, v73, v65
	v_mul_f32_e32 v65, v156, v65
	v_mul_f32_e32 v66, v66, v67
	v_add_f32_e32 v67, 1.0, v69
	v_rcp_f32_e32 v67, v67
	v_mul_f32_e32 v66, v74, v66
	s_waitcnt vmcnt(6)
	v_mul_f32_e32 v64, v96, v64
	v_mul_f32_e32 v65, v97, v65
	v_mul_f32_e32 v67, v67, v68
	v_lshlrev_b32_e32 v68, 16, v110
	v_mul_f32_e32 v69, 0xbfb8aa3b, v68
	v_mul_f32_e32 v67, v75, v67
	v_exp_f32_e32 v69, v69
	v_mul_f32_e32 v66, v156, v66
	v_mul_f32_e32 v67, v156, v67
	v_mul_f32_e32 v66, v98, v66
	v_mul_f32_e32 v67, v99, v67
	v_cvt_pk_bf16_f32 v64, v64, v65
	v_cvt_pk_bf16_f32 v65, v66, v67
	v_mov_b64_e32 v[242:243], v[64:65]
	v_and_b32_e32 v65, 0xffff0000, v110
	v_add_f32_e32 v64, 1.0, v69
	v_mul_f32_e32 v66, 0xbfb8aa3b, v65
	v_rcp_f32_e32 v64, v64
	v_exp_f32_e32 v66, v66
	v_lshlrev_b32_e32 v67, 16, v111
	v_mul_f32_e32 v64, v64, v68
	v_add_f32_e32 v66, 1.0, v66
	v_mul_f32_e32 v68, 0xbfb8aa3b, v67
	v_rcp_f32_e32 v66, v66
	v_exp_f32_e32 v68, v68
	v_mul_f32_e32 v64, v76, v64
	v_mul_f32_e32 v64, v156, v64
	v_mul_f32_e32 v65, v66, v65
	v_add_f32_e32 v66, 1.0, v68
	v_and_b32_e32 v68, 0xffff0000, v111
	v_mul_f32_e32 v69, 0xbfb8aa3b, v68
	v_rcp_f32_e32 v66, v66
	v_exp_f32_e32 v69, v69
	v_mul_f32_e32 v65, v77, v65
	v_mul_f32_e32 v65, v156, v65
	v_mul_f32_e32 v66, v66, v67
	v_add_f32_e32 v67, 1.0, v69
	v_rcp_f32_e32 v67, v67
	v_mul_f32_e32 v66, v78, v66
	s_waitcnt vmcnt(5)
	v_mul_f32_e32 v64, v100, v64
	v_mul_f32_e32 v65, v101, v65
	v_mul_f32_e32 v67, v67, v68
	v_lshlrev_b32_e32 v68, 16, v86
	v_mul_f32_e32 v69, 0xbfb8aa3b, v68
	v_exp_f32_e32 v69, v69
	v_mul_f32_e32 v67, v79, v67
	v_mul_f32_e32 v66, v156, v66
	v_mul_f32_e32 v67, v156, v67
	v_mul_f32_e32 v66, v102, v66
	v_mul_f32_e32 v67, v103, v67
	v_cvt_pk_bf16_f32 v64, v64, v65
	v_cvt_pk_bf16_f32 v65, v66, v67
	v_mov_b64_e32 v[244:245], v[64:65]
	s_nop 1
	v_permlane32_swap_b32_e32 v242, v244
	v_permlane32_swap_b32_e32 v243, v245
	global_store_dwordx4 v[206:207], v[242:245], off offset:288
	v_add_f32_e32 v64, 1.0, v69
	v_and_b32_e32 v65, 0xffff0000, v86
	v_rcp_f32_e32 v64, v64
	v_mul_f32_e32 v66, 0xbfb8aa3b, v65
	v_exp_f32_e32 v66, v66
	v_mul_f32_e32 v64, v64, v68
	v_mul_f32_e32 v32, v32, v64
	v_add_f32_e32 v64, 1.0, v66
	v_rcp_f32_e32 v64, v64
	v_mul_f32_e32 v32, v156, v32
	v_lshlrev_b32_e32 v66, 16, v87
	v_mul_f32_e32 v67, 0xbfb8aa3b, v66
	s_waitcnt vmcnt(5)
	v_mul_f32_e32 v32, v60, v32
	v_mul_f32_e32 v60, v64, v65
	v_and_b32_e32 v64, 0xffff0000, v87
	v_exp_f32_e32 v67, v67
	v_mul_f32_e32 v65, 0xbfb8aa3b, v64
	v_exp_f32_e32 v65, v65
	v_mul_f32_e32 v33, v33, v60
	v_add_f32_e32 v60, 1.0, v67
	v_mul_f32_e32 v33, v156, v33
	v_rcp_f32_e32 v60, v60
	v_mul_f32_e32 v33, v61, v33
	v_add_f32_e32 v61, 1.0, v65
	v_rcp_f32_e32 v61, v61
	v_mul_f32_e32 v60, v60, v66
	v_mul_f32_e32 v34, v34, v60
	v_mul_f32_e32 v34, v156, v34
	v_mul_f32_e32 v60, v61, v64
	v_mul_f32_e32 v35, v35, v60
	v_lshlrev_b32_e32 v60, 16, v84
	v_mul_f32_e32 v61, 0xbfb8aa3b, v60
	v_exp_f32_e32 v61, v61
	v_mul_f32_e32 v35, v156, v35
	v_mul_f32_e32 v34, v62, v34
	v_mul_f32_e32 v35, v63, v35
	v_cvt_pk_bf16_f32 v32, v32, v33
	v_cvt_pk_bf16_f32 v33, v34, v35
	v_mov_b64_e32 v[246:247], v[32:33]
	v_add_f32_e32 v32, 1.0, v61
	v_and_b32_e32 v33, 0xffff0000, v84
	v_rcp_f32_e32 v32, v32
	v_mul_f32_e32 v34, 0xbfb8aa3b, v33
	v_exp_f32_e32 v34, v34
	v_lshlrev_b32_e32 v35, 16, v85
	v_mul_f32_e32 v32, v32, v60
	v_mul_f32_e32 v32, v36, v32
	v_add_f32_e32 v34, 1.0, v34
	v_mul_f32_e32 v36, 0xbfb8aa3b, v35
	v_rcp_f32_e32 v34, v34
	v_exp_f32_e32 v36, v36
	v_mul_f32_e32 v32, v156, v32
	s_waitcnt vmcnt(4)
	v_mul_f32_e32 v32, v56, v32
	v_mul_f32_e32 v33, v34, v33
	v_add_f32_e32 v34, 1.0, v36
	v_and_b32_e32 v36, 0xffff0000, v85
	v_mul_f32_e32 v33, v37, v33
	v_mul_f32_e32 v37, 0xbfb8aa3b, v36
	v_rcp_f32_e32 v34, v34
	v_exp_f32_e32 v37, v37
	v_mul_f32_e32 v33, v156, v33
	v_mul_f32_e32 v33, v57, v33
	v_mul_f32_e32 v34, v34, v35
	v_add_f32_e32 v35, 1.0, v37
	v_rcp_f32_e32 v35, v35
	v_mul_f32_e32 v34, v38, v34
	v_mul_f32_e32 v34, v156, v34
	v_mul_f32_e32 v34, v58, v34
	v_mul_f32_e32 v35, v35, v36
	v_lshlrev_b32_e32 v36, 16, v82
	v_mul_f32_e32 v37, 0xbfb8aa3b, v36
	v_mul_f32_e32 v35, v39, v35
	v_exp_f32_e32 v37, v37
	v_mul_f32_e32 v35, v156, v35
	v_mul_f32_e32 v35, v59, v35
	v_cvt_pk_bf16_f32 v32, v32, v33
	v_cvt_pk_bf16_f32 v33, v34, v35
	v_mov_b64_e32 v[248:249], v[32:33]
	s_nop 1
	v_permlane32_swap_b32_e32 v246, v248
	v_permlane32_swap_b32_e32 v247, v249
	global_store_dwordx4 v[206:207], v[246:249], off offset:320
	v_and_b32_e32 v33, 0xffff0000, v82
	v_add_f32_e32 v32, 1.0, v37
	v_mul_f32_e32 v34, 0xbfb8aa3b, v33
	v_rcp_f32_e32 v32, v32
	v_exp_f32_e32 v34, v34
	v_lshlrev_b32_e32 v35, 16, v83
	v_mul_f32_e32 v32, v32, v36
	v_add_f32_e32 v34, 1.0, v34
	v_mul_f32_e32 v36, 0xbfb8aa3b, v35
	v_rcp_f32_e32 v34, v34
	v_exp_f32_e32 v36, v36
	v_mul_f32_e32 v32, v40, v32
	v_mul_f32_e32 v32, v156, v32
	v_mul_f32_e32 v33, v34, v33
	v_add_f32_e32 v34, 1.0, v36
	v_and_b32_e32 v36, 0xffff0000, v83
	v_mul_f32_e32 v37, 0xbfb8aa3b, v36
	v_rcp_f32_e32 v34, v34
	v_exp_f32_e32 v37, v37
	v_mul_f32_e32 v33, v41, v33
	v_mul_f32_e32 v33, v156, v33
	v_mul_f32_e32 v34, v34, v35
	v_add_f32_e32 v35, 1.0, v37
	v_rcp_f32_e32 v35, v35
	v_mul_f32_e32 v34, v42, v34
	s_waitcnt vmcnt(4)
	v_mul_f32_e32 v32, v52, v32
	v_mul_f32_e32 v33, v53, v33
	v_mul_f32_e32 v35, v35, v36
	v_lshlrev_b32_e32 v36, 16, v80
	v_mul_f32_e32 v37, 0xbfb8aa3b, v36
	v_mul_f32_e32 v35, v43, v35
	v_exp_f32_e32 v37, v37
	v_mul_f32_e32 v34, v156, v34
	v_mul_f32_e32 v35, v156, v35
	v_mul_f32_e32 v34, v54, v34
	v_mul_f32_e32 v35, v55, v35
	v_cvt_pk_bf16_f32 v32, v32, v33
	v_cvt_pk_bf16_f32 v33, v34, v35
	v_mov_b64_e32 v[230:231], v[32:33]
	v_and_b32_e32 v33, 0xffff0000, v80
	v_add_f32_e32 v32, 1.0, v37
	v_mul_f32_e32 v34, 0xbfb8aa3b, v33
	v_rcp_f32_e32 v32, v32
	v_exp_f32_e32 v34, v34
	v_lshlrev_b32_e32 v35, 16, v81
	v_mul_f32_e32 v32, v32, v36
	v_add_f32_e32 v34, 1.0, v34
	v_mul_f32_e32 v36, 0xbfb8aa3b, v35
	v_rcp_f32_e32 v34, v34
	v_exp_f32_e32 v36, v36
	v_mul_f32_e32 v32, v44, v32
	v_mul_f32_e32 v32, v156, v32
	v_mul_f32_e32 v33, v34, v33
	v_add_f32_e32 v34, 1.0, v36
	v_and_b32_e32 v36, 0xffff0000, v81
	v_mul_f32_e32 v37, 0xbfb8aa3b, v36
	v_rcp_f32_e32 v34, v34
	v_exp_f32_e32 v37, v37
	v_mul_f32_e32 v33, v45, v33
	v_mul_f32_e32 v33, v156, v33
	v_mul_f32_e32 v34, v34, v35
	v_add_f32_e32 v35, 1.0, v37
	v_rcp_f32_e32 v35, v35
	v_mul_f32_e32 v34, v46, v34
	s_waitcnt vmcnt(3)
	v_mul_f32_e32 v32, v48, v32
	v_mul_f32_e32 v33, v49, v33
	v_mul_f32_e32 v35, v35, v36
	v_mul_f32_e32 v35, v47, v35
	v_mul_f32_e32 v34, v156, v34
	v_mul_f32_e32 v35, v156, v35
	v_mul_f32_e32 v34, v50, v34
	v_mul_f32_e32 v35, v51, v35
	v_cvt_pk_bf16_f32 v32, v32, v33
	v_cvt_pk_bf16_f32 v33, v34, v35
	v_permlane32_swap_b32_e32 v210, v212
	v_permlane32_swap_b32_e32 v211, v213
	v_permlane32_swap_b32_e32 v216, v218
	v_permlane32_swap_b32_e32 v217, v219
	v_permlane32_swap_b32_e32 v220, v222
	v_permlane32_swap_b32_e32 v221, v223
	v_permlane32_swap_b32_e32 v224, v226
	v_permlane32_swap_b32_e32 v225, v227
	v_mov_b64_e32 v[72:73], v[210:211]
	v_mov_b64_e32 v[74:75], v[212:213]
	v_mov_b64_e32 v[76:77], v[216:217]
	v_mov_b64_e32 v[78:79], v[218:219]
	v_mov_b64_e32 v[54:55], v[220:221]
	v_mov_b64_e32 v[52:53], v[222:223]
	v_mov_b64_e32 v[50:51], v[224:225]
	v_mov_b64_e32 v[48:49], v[226:227]
	v_lshlrev_b32_e32 v80, 16, v72
	v_mov_b64_e32 v[232:233], v[32:33]
	s_nop 1
	v_permlane32_swap_b32_e32 v230, v232
	v_permlane32_swap_b32_e32 v231, v233
	global_store_dwordx4 v[206:207], v[230:233], off offset:352
	global_load_dwordx4 v[56:59], v[146:147], off offset:768
	global_load_dwordx4 v[60:63], v[146:147], off offset:800
	global_load_dwordx4 v[64:67], v[146:147], off offset:832
	global_load_dwordx4 v[68:71], v[146:147], off offset:864
	global_load_dwordx4 v[44:47], v[146:147], off offset:896
	global_load_dwordx4 v[40:43], v[146:147], off offset:928
	v_mul_f32_e32 v32, 0xbfb8aa3b, v80
	v_exp_f32_e32 v81, v32
	v_and_b32_e32 v72, 0xffff0000, v72
	v_mul_f32_e32 v82, 0xbfb8aa3b, v72
	v_exp_f32_e32 v82, v82
	v_add_f32_e32 v81, 1.0, v81
	v_rcp_f32_e32 v81, v81
	global_load_dwordx4 v[36:39], v[146:147], off offset:960
	global_load_dwordx4 v[32:35], v[146:147], off offset:992
	v_mul_f32_e32 v80, v81, v80
	v_mul_f32_e32 v16, v16, v80
	v_add_f32_e32 v80, 1.0, v82
	v_rcp_f32_e32 v80, v80
	v_mul_f32_e32 v16, v156, v16
	v_lshlrev_b32_e32 v81, 16, v73
	v_mul_f32_e32 v82, 0xbfb8aa3b, v81
	v_exp_f32_e32 v82, v82
	s_waitcnt vmcnt(7)
	v_mul_f32_e32 v16, v56, v16
	v_mul_f32_e32 v56, v80, v72
	v_and_b32_e32 v72, 0xffff0000, v73
	v_mul_f32_e32 v73, 0xbfb8aa3b, v72
	v_exp_f32_e32 v73, v73
	v_mul_f32_e32 v17, v17, v56
	v_add_f32_e32 v56, 1.0, v82
	v_mul_f32_e32 v17, v156, v17
	v_rcp_f32_e32 v56, v56
	v_mul_f32_e32 v17, v57, v17
	v_add_f32_e32 v57, 1.0, v73
	v_rcp_f32_e32 v57, v57
	v_mul_f32_e32 v56, v56, v81
	v_mul_f32_e32 v18, v18, v56
	v_mul_f32_e32 v18, v156, v18
	v_mul_f32_e32 v56, v57, v72
	v_mul_f32_e32 v19, v19, v56
	v_lshlrev_b32_e32 v56, 16, v74
	v_mul_f32_e32 v57, 0xbfb8aa3b, v56
	v_exp_f32_e32 v57, v57
	v_mul_f32_e32 v19, v156, v19
	v_mul_f32_e32 v18, v58, v18
	v_mul_f32_e32 v19, v59, v19
	v_cvt_pk_bf16_f32 v16, v16, v17
	v_cvt_pk_bf16_f32 v17, v18, v19
	v_mov_b64_e32 v[238:239], v[16:17]
	v_add_f32_e32 v16, 1.0, v57
	v_and_b32_e32 v17, 0xffff0000, v74
	v_rcp_f32_e32 v16, v16
	v_mul_f32_e32 v18, 0xbfb8aa3b, v17
	v_exp_f32_e32 v18, v18
	v_lshlrev_b32_e32 v19, 16, v75
	v_mul_f32_e32 v16, v16, v56
	v_mul_f32_e32 v16, v20, v16
	v_add_f32_e32 v18, 1.0, v18
	v_mul_f32_e32 v20, 0xbfb8aa3b, v19
	v_rcp_f32_e32 v18, v18
	v_exp_f32_e32 v20, v20
	v_mul_f32_e32 v16, v156, v16
	s_waitcnt vmcnt(6)
	v_mul_f32_e32 v16, v60, v16
	v_mul_f32_e32 v17, v18, v17
	v_add_f32_e32 v18, 1.0, v20
	v_and_b32_e32 v20, 0xffff0000, v75
	v_mul_f32_e32 v17, v21, v17
	v_mul_f32_e32 v21, 0xbfb8aa3b, v20
	v_rcp_f32_e32 v18, v18
	v_exp_f32_e32 v21, v21
	v_mul_f32_e32 v17, v156, v17
	v_mul_f32_e32 v17, v61, v17
	v_mul_f32_e32 v18, v18, v19
	v_add_f32_e32 v19, 1.0, v21
	v_rcp_f32_e32 v19, v19
	v_mul_f32_e32 v18, v22, v18
	v_mul_f32_e32 v18, v156, v18
	v_mul_f32_e32 v18, v62, v18
	v_mul_f32_e32 v19, v19, v20
	v_lshlrev_b32_e32 v20, 16, v76
	v_mul_f32_e32 v21, 0xbfb8aa3b, v20
	v_mul_f32_e32 v19, v23, v19
	v_exp_f32_e32 v21, v21
	v_mul_f32_e32 v19, v156, v19
	v_mul_f32_e32 v19, v63, v19
	v_cvt_pk_bf16_f32 v16, v16, v17
	v_cvt_pk_bf16_f32 v17, v18, v19
	v_mov_b64_e32 v[240:241], v[16:17]
	s_nop 1
	v_permlane32_swap_b32_e32 v238, v240
	v_permlane32_swap_b32_e32 v239, v241
	global_store_dwordx4 v[206:207], v[238:241], off offset:384
	v_and_b32_e32 v17, 0xffff0000, v76
	v_add_f32_e32 v16, 1.0, v21
	v_mul_f32_e32 v18, 0xbfb8aa3b, v17
	v_rcp_f32_e32 v16, v16
	v_exp_f32_e32 v18, v18
	v_lshlrev_b32_e32 v19, 16, v77
	v_mul_f32_e32 v16, v16, v20
	v_add_f32_e32 v18, 1.0, v18
	v_mul_f32_e32 v20, 0xbfb8aa3b, v19
	v_rcp_f32_e32 v18, v18
	v_exp_f32_e32 v20, v20
	v_mul_f32_e32 v16, v24, v16
	v_mul_f32_e32 v16, v156, v16
	v_mul_f32_e32 v17, v18, v17
	v_add_f32_e32 v18, 1.0, v20
	v_and_b32_e32 v20, 0xffff0000, v77
	v_mul_f32_e32 v21, 0xbfb8aa3b, v20
	v_rcp_f32_e32 v18, v18
	v_exp_f32_e32 v21, v21
	v_mul_f32_e32 v17, v25, v17
	v_mul_f32_e32 v17, v156, v17
	v_mul_f32_e32 v18, v18, v19
	v_add_f32_e32 v19, 1.0, v21
	v_rcp_f32_e32 v19, v19
	v_mul_f32_e32 v18, v26, v18
	s_waitcnt vmcnt(6)
	v_mul_f32_e32 v16, v64, v16
	v_mul_f32_e32 v17, v65, v17
	v_mul_f32_e32 v19, v19, v20
	v_lshlrev_b32_e32 v20, 16, v78
	v_mul_f32_e32 v21, 0xbfb8aa3b, v20
	v_mul_f32_e32 v19, v27, v19
	v_exp_f32_e32 v21, v21
	v_mul_f32_e32 v18, v156, v18
	v_mul_f32_e32 v19, v156, v19
	v_mul_f32_e32 v18, v66, v18
	v_mul_f32_e32 v19, v67, v19
	v_cvt_pk_bf16_f32 v16, v16, v17
	v_cvt_pk_bf16_f32 v17, v18, v19
	v_mov_b64_e32 v[242:243], v[16:17]
	v_and_b32_e32 v17, 0xffff0000, v78
	v_add_f32_e32 v16, 1.0, v21
	v_mul_f32_e32 v18, 0xbfb8aa3b, v17
	v_rcp_f32_e32 v16, v16
	v_exp_f32_e32 v18, v18
	v_lshlrev_b32_e32 v19, 16, v79
	v_mul_f32_e32 v16, v16, v20
	v_add_f32_e32 v18, 1.0, v18
	v_mul_f32_e32 v20, 0xbfb8aa3b, v19
	v_rcp_f32_e32 v18, v18
	v_exp_f32_e32 v20, v20
	v_mul_f32_e32 v16, v28, v16
	v_mul_f32_e32 v16, v156, v16
	v_mul_f32_e32 v17, v18, v17
	v_add_f32_e32 v18, 1.0, v20
	v_and_b32_e32 v20, 0xffff0000, v79
	v_mul_f32_e32 v21, 0xbfb8aa3b, v20
	v_rcp_f32_e32 v18, v18
	v_exp_f32_e32 v21, v21
	v_mul_f32_e32 v17, v29, v17
	v_mul_f32_e32 v17, v156, v17
	v_mul_f32_e32 v18, v18, v19
	v_add_f32_e32 v19, 1.0, v21
	v_rcp_f32_e32 v19, v19
	v_mul_f32_e32 v18, v30, v18
	s_waitcnt vmcnt(5)
	v_mul_f32_e32 v16, v68, v16
	v_mul_f32_e32 v17, v69, v17
	v_mul_f32_e32 v19, v19, v20
	v_lshlrev_b32_e32 v20, 16, v54
	v_mul_f32_e32 v21, 0xbfb8aa3b, v20
	v_exp_f32_e32 v21, v21
	v_mul_f32_e32 v19, v31, v19
	v_mul_f32_e32 v18, v156, v18
	v_mul_f32_e32 v19, v156, v19
	v_mul_f32_e32 v18, v70, v18
	v_mul_f32_e32 v19, v71, v19
	v_cvt_pk_bf16_f32 v16, v16, v17
	v_cvt_pk_bf16_f32 v17, v18, v19
	v_mov_b64_e32 v[244:245], v[16:17]
	s_nop 1
	v_permlane32_swap_b32_e32 v242, v244
	v_permlane32_swap_b32_e32 v243, v245
	global_store_dwordx4 v[206:207], v[242:245], off offset:416
	v_add_f32_e32 v16, 1.0, v21
	v_and_b32_e32 v17, 0xffff0000, v54
	v_rcp_f32_e32 v16, v16
	v_mul_f32_e32 v18, 0xbfb8aa3b, v17
	v_exp_f32_e32 v18, v18
	v_mul_f32_e32 v16, v16, v20
	v_mul_f32_e32 v0, v0, v16
	v_add_f32_e32 v16, 1.0, v18
	v_lshlrev_b32_e32 v18, 16, v55
	v_rcp_f32_e32 v16, v16
	v_mul_f32_e32 v19, 0xbfb8aa3b, v18
	v_exp_f32_e32 v19, v19
	v_mul_f32_e32 v0, v156, v0
	v_mul_f32_e32 v16, v16, v17
	v_and_b32_e32 v17, 0xffff0000, v55
	v_mul_f32_e32 v1, v1, v16
	v_add_f32_e32 v16, 1.0, v19
	v_mul_f32_e32 v19, 0xbfb8aa3b, v17
	v_rcp_f32_e32 v16, v16
	v_exp_f32_e32 v19, v19
	v_mul_f32_e32 v1, v156, v1
	s_waitcnt vmcnt(5)
	v_mul_f32_e32 v0, v44, v0
	v_mul_f32_e32 v16, v16, v18
	v_add_f32_e32 v18, 1.0, v19
	v_rcp_f32_e32 v18, v18
	v_mul_f32_e32 v2, v2, v16
	v_mul_f32_e32 v1, v45, v1
	v_mul_f32_e32 v2, v156, v2
	v_mul_f32_e32 v16, v18, v17
	v_mul_f32_e32 v3, v3, v16
	v_lshlrev_b32_e32 v16, 16, v52
	v_mul_f32_e32 v17, 0xbfb8aa3b, v16
	v_exp_f32_e32 v17, v17
	v_mul_f32_e32 v3, v156, v3
	v_mul_f32_e32 v2, v46, v2
	v_mul_f32_e32 v3, v47, v3
	v_cvt_pk_bf16_f32 v0, v0, v1
	v_cvt_pk_bf16_f32 v1, v2, v3
	v_mov_b64_e32 v[246:247], v[0:1]
	v_add_f32_e32 v0, 1.0, v17
	v_and_b32_e32 v1, 0xffff0000, v52
	v_rcp_f32_e32 v0, v0
	v_mul_f32_e32 v2, 0xbfb8aa3b, v1
	v_exp_f32_e32 v2, v2
	v_lshlrev_b32_e32 v3, 16, v53
	v_mul_f32_e32 v0, v0, v16
	v_mul_f32_e32 v0, v4, v0
	v_add_f32_e32 v2, 1.0, v2
	v_mul_f32_e32 v4, 0xbfb8aa3b, v3
	v_rcp_f32_e32 v2, v2
	v_exp_f32_e32 v4, v4
	v_mul_f32_e32 v0, v156, v0
	s_waitcnt vmcnt(4)
	v_mul_f32_e32 v0, v40, v0
	v_mul_f32_e32 v1, v2, v1
	v_add_f32_e32 v2, 1.0, v4
	v_and_b32_e32 v4, 0xffff0000, v53
	v_mul_f32_e32 v1, v5, v1
	v_mul_f32_e32 v5, 0xbfb8aa3b, v4
	v_rcp_f32_e32 v2, v2
	v_exp_f32_e32 v5, v5
	v_mul_f32_e32 v1, v156, v1
	v_mul_f32_e32 v1, v41, v1
	v_mul_f32_e32 v2, v2, v3
	v_add_f32_e32 v3, 1.0, v5
	v_rcp_f32_e32 v3, v3
	v_mul_f32_e32 v2, v6, v2
	v_mul_f32_e32 v2, v156, v2
	v_mul_f32_e32 v2, v42, v2
	v_mul_f32_e32 v3, v3, v4
	v_lshlrev_b32_e32 v4, 16, v50
	v_mul_f32_e32 v5, 0xbfb8aa3b, v4
	v_mul_f32_e32 v3, v7, v3
	v_exp_f32_e32 v5, v5
	v_mul_f32_e32 v3, v156, v3
	v_mul_f32_e32 v3, v43, v3
	v_cvt_pk_bf16_f32 v0, v0, v1
	v_cvt_pk_bf16_f32 v1, v2, v3
	v_mov_b64_e32 v[248:249], v[0:1]
	s_nop 1
	v_permlane32_swap_b32_e32 v246, v248
	v_permlane32_swap_b32_e32 v247, v249
	global_store_dwordx4 v[206:207], v[246:249], off offset:448
	v_and_b32_e32 v1, 0xffff0000, v50
	v_add_f32_e32 v0, 1.0, v5
	v_mul_f32_e32 v2, 0xbfb8aa3b, v1
	v_rcp_f32_e32 v0, v0
	v_exp_f32_e32 v2, v2
	v_lshlrev_b32_e32 v3, 16, v51
	v_mul_f32_e32 v0, v0, v4
	v_add_f32_e32 v2, 1.0, v2
	v_mul_f32_e32 v4, 0xbfb8aa3b, v3
	v_rcp_f32_e32 v2, v2
	v_exp_f32_e32 v4, v4
	v_mul_f32_e32 v0, v8, v0
	v_mul_f32_e32 v0, v156, v0
	v_mul_f32_e32 v1, v2, v1
	v_add_f32_e32 v2, 1.0, v4
	v_and_b32_e32 v4, 0xffff0000, v51
	v_mul_f32_e32 v5, 0xbfb8aa3b, v4
	v_rcp_f32_e32 v2, v2
	v_exp_f32_e32 v5, v5
	v_mul_f32_e32 v1, v9, v1
	v_mul_f32_e32 v1, v156, v1
	v_mul_f32_e32 v2, v2, v3
	v_add_f32_e32 v3, 1.0, v5
	v_rcp_f32_e32 v3, v3
	v_mul_f32_e32 v2, v10, v2
	s_waitcnt vmcnt(4)
	v_mul_f32_e32 v0, v36, v0
	v_mul_f32_e32 v1, v37, v1
	v_mul_f32_e32 v3, v3, v4
	v_lshlrev_b32_e32 v4, 16, v48
	v_mul_f32_e32 v5, 0xbfb8aa3b, v4
	v_mul_f32_e32 v3, v11, v3
	v_exp_f32_e32 v5, v5
	v_mul_f32_e32 v2, v156, v2
	v_mul_f32_e32 v3, v156, v3
	v_mul_f32_e32 v2, v38, v2
	v_mul_f32_e32 v3, v39, v3
	v_cvt_pk_bf16_f32 v0, v0, v1
	v_cvt_pk_bf16_f32 v1, v2, v3
	v_mov_b64_e32 v[230:231], v[0:1]
	v_and_b32_e32 v1, 0xffff0000, v48
	v_add_f32_e32 v0, 1.0, v5
	v_mul_f32_e32 v2, 0xbfb8aa3b, v1
	v_rcp_f32_e32 v0, v0
	v_exp_f32_e32 v2, v2
	v_lshlrev_b32_e32 v3, 16, v49
	v_mul_f32_e32 v0, v0, v4
	v_add_f32_e32 v2, 1.0, v2
	v_mul_f32_e32 v4, 0xbfb8aa3b, v3
	v_rcp_f32_e32 v2, v2
	v_exp_f32_e32 v4, v4
	v_mul_f32_e32 v0, v12, v0
	v_mul_f32_e32 v0, v156, v0
	v_mul_f32_e32 v1, v2, v1
	v_add_f32_e32 v2, 1.0, v4
	v_and_b32_e32 v4, 0xffff0000, v49
	v_mul_f32_e32 v5, 0xbfb8aa3b, v4
	v_rcp_f32_e32 v2, v2
	v_exp_f32_e32 v5, v5
	v_mul_f32_e32 v1, v13, v1
	v_mul_f32_e32 v1, v156, v1
	v_mul_f32_e32 v2, v2, v3
	v_add_f32_e32 v3, 1.0, v5
	v_rcp_f32_e32 v3, v3
	v_mul_f32_e32 v2, v14, v2
	s_waitcnt vmcnt(3)
	v_mul_f32_e32 v0, v32, v0
	v_mul_f32_e32 v1, v33, v1
	v_mul_f32_e32 v3, v3, v4
	v_mul_f32_e32 v3, v15, v3
	v_mul_f32_e32 v2, v156, v2
	v_mul_f32_e32 v3, v156, v3
	v_mul_f32_e32 v2, v34, v2
	v_mul_f32_e32 v3, v35, v3
	v_cvt_pk_bf16_f32 v0, v0, v1
	v_cvt_pk_bf16_f32 v1, v2, v3
	v_mov_b64_e32 v[232:233], v[0:1]
	s_nop 1
	v_permlane32_swap_b32_e32 v230, v232
	v_permlane32_swap_b32_e32 v231, v233
	global_store_dwordx4 v[206:207], v[230:233], off offset:480
	s_cbranch_scc1 .LBB0_700
